# FFN-up epilogue: act written with one 16-byte store per lane (n=0 results held in dead val registers)
# speedup vs baseline: 1.1552x; 1.0031x over previous
; DEV void grid_barrier(unsigned* cnt, const unsigned target, const int tid) {
;     asm volatile("s_waitcnt vmcnt(0)" ::: "memory");
;     __syncthreads();
;     if (tid == 0) {
;         __builtin_amdgcn_fence(__ATOMIC_RELEASE, "agent");
;         __hip_atomic_fetch_add(cnt, 1u, __ATOMIC_RELAXED, __HIP_MEMORY_SCOPE_AGENT);
;         while (__hip_atomic_load(cnt, __ATOMIC_RELAXED, __HIP_MEMORY_SCOPE_AGENT) < target) __builtin_amdgcn_s_sleep(28);
;         __builtin_amdgcn_fence(__ATOMIC_ACQUIRE, "agent");
;         asm volatile("s_waitcnt vmcnt(0)" ::: "memory");
;     }
;     __syncthreads();
; }
.Lgb0_follow:
.Lgb0_poll:
	global_load_dword v4, v2, s[4:5] offset:32 sc1
	s_waitcnt vmcnt(0)
	v_cmp_gt_u32_e32 vcc, s7, v4
	s_cbranch_vccz .Lgb0_done
	s_sleep 8
	s_branch .Lgb0_poll

; DEV void grid_barrier(unsigned* cnt, const unsigned target, const int tid) {
;     asm volatile("s_waitcnt vmcnt(0)" ::: "memory");
;     __syncthreads();
;     if (tid == 0) {
;         __builtin_amdgcn_fence(__ATOMIC_RELEASE, "agent");
;         __hip_atomic_fetch_add(cnt, 1u, __ATOMIC_RELAXED, __HIP_MEMORY_SCOPE_AGENT);
;         while (__hip_atomic_load(cnt, __ATOMIC_RELAXED, __HIP_MEMORY_SCOPE_AGENT) < target) __builtin_amdgcn_s_sleep(28);
;         __builtin_amdgcn_fence(__ATOMIC_ACQUIRE, "agent");
;         asm volatile("s_waitcnt vmcnt(0)" ::: "memory");
;     }
;     __syncthreads();
; }
.Lgb1_follow:
.Lgb1_poll:
	global_load_dword v4, v2, s[4:5] offset:64 sc1
	s_waitcnt vmcnt(0)
	v_cmp_gt_u32_e32 vcc, s7, v4
	s_cbranch_vccz .Lgb1_done
	s_sleep 8
	s_branch .Lgb1_poll

; DEV unsigned cvt_pk_bf16(float lo, float hi) { unsigned r; asm volatile("v_cvt_pk_bf16_f32 %0, %1, %2" : "=v"(r) : "v"(lo), "v"(hi)); return r; }
; #define ROR1(x) __int_as_float(__builtin_amdgcn_update_dpp(0, __float_as_int(x), 0x121, 0xf, 0xf, false))
; #define ROR15(x) __int_as_float(__builtin_amdgcn_update_dpp(0, __float_as_int(x), 0x12F, 0xf, 0xf, false))
;     DEV void operator()(const Acc& acc, const Unit& u, int wr, int wc, int fr, int fq, LAS unsigned char* misc) const {
;     ...
;                 for (int m = 0; m < 4; ++m) {
;                     f32x4 Rm, Dnext = bdn;
; #pragma unroll
;                     for (int e = 0; e < 4; ++e) { Rm[e] = ROR1(acc[ai][0][m][n][e]); if (m < 3) Dnext[e] = ROR15(acc[ai][0][m < 3 ? m + 1 : 3][n][e]); }
;                     const f32x4 up = (fr > 0) ? Rm : Rprev;
;                     const f32x4 dn = (fr < 15) ? Dcur : Dnext;
;                     Rprev = Rm; Dcur = Dnext;
;                     const int rr = q * 64 + m * 16 + fr, sq = s0 + rr;
;                     const f32x4 g = acc[ai][0][m][n], v = acc[ai][1][m][n];
;                     f32x4 o;
; #pragma unroll
;                     for (int e = 0; e < 4; ++e) { const float z = w0[e] * up[e] + w1[e] * g[e] + w2[e] * dn[e] + bb[e]; o[e] = z * __builtin_amdgcn_rcpf(1.f + __builtin_amdgcn_exp2f(-1.4426950408889634f * z)) * v[e]; }
;                     if (rr >= 1 && rr <= 254) { u32x2 w; w.x = cvt_pk_bf16(o[0], o[1]); w.y = cvt_pk_bf16(o[2], o[3]);
;                         *(u32x2*)(act + (size_t)(sbase + sq) * DFF + j) = w; }
.LffnA_ns_3:
	v_mov_b32_dpp v150, v138 row_ror:1 row_mask:0xf bank_mask:0xf
	v_mov_b32_dpp v151, v139 row_ror:1 row_mask:0xf bank_mask:0xf
	v_mov_b32_dpp v152, v140 row_ror:1 row_mask:0xf bank_mask:0xf
	v_mov_b32_dpp v153, v141 row_ror:1 row_mask:0xf bank_mask:0xf
	v_mov_b32_dpp v202, v134 row_ror:15 row_mask:0xf bank_mask:0xf
	v_mov_b32_dpp v203, v135 row_ror:15 row_mask:0xf bank_mask:0xf
	v_mov_b32_dpp v204, v136 row_ror:15 row_mask:0xf bank_mask:0xf
	v_mov_b32_dpp v205, v137 row_ror:15 row_mask:0xf bank_mask:0xf
	s_waitcnt lgkmcnt(0)
	v_cndmask_b32_e64 v206, v150, v146, s[8:9]
	v_cndmask_b32_e64 v207, v151, v147, s[8:9]
	v_cndmask_b32_e64 v208, v152, v148, s[8:9]
	v_cndmask_b32_e64 v209, v153, v149, s[8:9]
	ds_read_b128 v[146:149], v176 offset:3072
	v_cndmask_b32_e64 v210, v198, v202, s[10:11]
	v_cndmask_b32_e64 v211, v199, v203, s[10:11]
	v_cndmask_b32_e64 v212, v200, v204, s[10:11]
	v_cndmask_b32_e64 v213, v201, v205, s[10:11]
	v_mul_f32_e32 v138, v110, v138
	v_mul_f32_e32 v139, v111, v139
	v_mul_f32_e32 v140, v112, v140
	v_mul_f32_e32 v141, v113, v141
	v_mul_f32_e32 v210, v114, v210
	v_mul_f32_e32 v211, v115, v211
	v_mul_f32_e32 v212, v116, v212
	v_mul_f32_e32 v213, v117, v213
	v_fmac_f32_e32 v138, v106, v206
	v_fmac_f32_e32 v139, v107, v207
	v_fmac_f32_e32 v140, v108, v208
	v_fmac_f32_e32 v141, v109, v209
	v_add_f32_e32 v138, v210, v138
	v_add_f32_e32 v139, v211, v139
	v_add_f32_e32 v140, v212, v140
	v_add_f32_e32 v141, v213, v141
	v_add_f32_e32 v138, v118, v138
	v_add_f32_e32 v139, v119, v139
	v_add_f32_e32 v140, v120, v140
	v_add_f32_e32 v141, v121, v141
	v_mul_f32_e32 v206, 0xbfb8aa3b, v138
	v_mul_f32_e32 v207, 0xbfb8aa3b, v139
	v_mul_f32_e32 v208, 0xbfb8aa3b, v140
	v_mul_f32_e32 v209, 0xbfb8aa3b, v141
	v_exp_f32_e32 v206, v206
	v_exp_f32_e32 v207, v207
	v_exp_f32_e32 v208, v208
	v_exp_f32_e32 v209, v209
	v_add_f32_e32 v206, 1.0, v206
	v_add_f32_e32 v207, 1.0, v207
	v_add_f32_e32 v208, 1.0, v208
	v_add_f32_e32 v209, 1.0, v209
	v_rcp_f32_e32 v206, v206
	v_rcp_f32_e32 v207, v207
	v_rcp_f32_e32 v208, v208
	v_rcp_f32_e32 v209, v209
	v_mul_f32_e32 v138, v138, v206
	v_mul_f32_e32 v139, v139, v207
	v_mul_f32_e32 v140, v140, v208
	v_mul_f32_e32 v141, v141, v209
	v_mul_f32_e32 v138, v142, v138
	v_mul_f32_e32 v139, v143, v139
	v_mul_f32_e32 v140, v144, v140
	v_mul_f32_e32 v141, v145, v141
	v_cvt_pk_bf16_f32 v142, v138, v139
	v_cvt_pk_bf16_f32 v143, v140, v141
	v_mov_b32_dpp v194, v134 row_ror:1 row_mask:0xf bank_mask:0xf
	v_mov_b32_dpp v195, v135 row_ror:1 row_mask:0xf bank_mask:0xf
	v_mov_b32_dpp v196, v136 row_ror:1 row_mask:0xf bank_mask:0xf
	v_mov_b32_dpp v197, v137 row_ror:1 row_mask:0xf bank_mask:0xf
	v_mov_b32_dpp v198, v126 row_ror:15 row_mask:0xf bank_mask:0xf
	v_mov_b32_dpp v199, v127 row_ror:15 row_mask:0xf bank_mask:0xf
	v_mov_b32_dpp v200, v128 row_ror:15 row_mask:0xf bank_mask:0xf
	v_mov_b32_dpp v201, v129 row_ror:15 row_mask:0xf bank_mask:0xf
	v_cndmask_b32_e64 v206, v194, v150, s[8:9]
	v_cndmask_b32_e64 v207, v195, v151, s[8:9]
	v_cndmask_b32_e64 v208, v196, v152, s[8:9]
	v_cndmask_b32_e64 v209, v197, v153, s[8:9]
	v_cndmask_b32_e64 v210, v202, v198, s[10:11]
	v_cndmask_b32_e64 v211, v203, v199, s[10:11]
	v_cndmask_b32_e64 v212, v204, v200, s[10:11]
	v_cndmask_b32_e64 v213, v205, v201, s[10:11]
	v_mul_f32_e32 v134, v110, v134
	v_mul_f32_e32 v135, v111, v135
	v_mul_f32_e32 v136, v112, v136
	v_mul_f32_e32 v137, v113, v137
	v_mul_f32_e32 v210, v114, v210
	v_mul_f32_e32 v211, v115, v211
	v_mul_f32_e32 v212, v116, v212
	v_mul_f32_e32 v213, v117, v213
	v_fmac_f32_e32 v134, v106, v206
	v_fmac_f32_e32 v135, v107, v207
	v_fmac_f32_e32 v136, v108, v208
	v_fmac_f32_e32 v137, v109, v209
	v_add_f32_e32 v134, v210, v134
	v_add_f32_e32 v135, v211, v135
	v_add_f32_e32 v136, v212, v136
	v_add_f32_e32 v137, v213, v137
	v_add_f32_e32 v134, v118, v134
	v_add_f32_e32 v135, v119, v135
	v_add_f32_e32 v136, v120, v136
	v_add_f32_e32 v137, v121, v137
	v_mul_f32_e32 v206, 0xbfb8aa3b, v134
	v_mul_f32_e32 v207, 0xbfb8aa3b, v135
	v_mul_f32_e32 v208, 0xbfb8aa3b, v136
	v_mul_f32_e32 v209, 0xbfb8aa3b, v137
	v_exp_f32_e32 v206, v206
	v_exp_f32_e32 v207, v207
	v_exp_f32_e32 v208, v208
	v_exp_f32_e32 v209, v209
	v_add_f32_e32 v206, 1.0, v206
	v_add_f32_e32 v207, 1.0, v207
	v_add_f32_e32 v208, 1.0, v208
	v_add_f32_e32 v209, 1.0, v209
	v_rcp_f32_e32 v206, v206
	v_rcp_f32_e32 v207, v207
	v_rcp_f32_e32 v208, v208
	v_rcp_f32_e32 v209, v209
	v_mul_f32_e32 v134, v134, v206
	v_mul_f32_e32 v135, v135, v207
	v_mul_f32_e32 v136, v136, v208
	v_mul_f32_e32 v137, v137, v209
	v_mul_f32_e32 v134, v130, v134
	v_mul_f32_e32 v135, v131, v135
	v_mul_f32_e32 v136, v132, v136
	v_mul_f32_e32 v137, v133, v137
	v_cvt_pk_bf16_f32 v130, v134, v135
	v_cvt_pk_bf16_f32 v131, v136, v137
	v_mov_b32_dpp v150, v126 row_ror:1 row_mask:0xf bank_mask:0xf
	v_mov_b32_dpp v151, v127 row_ror:1 row_mask:0xf bank_mask:0xf
	v_mov_b32_dpp v152, v128 row_ror:1 row_mask:0xf bank_mask:0xf
	v_mov_b32_dpp v153, v129 row_ror:1 row_mask:0xf bank_mask:0xf
	v_mov_b32_dpp v202, v98 row_ror:15 row_mask:0xf bank_mask:0xf
	v_mov_b32_dpp v203, v99 row_ror:15 row_mask:0xf bank_mask:0xf
	v_mov_b32_dpp v204, v100 row_ror:15 row_mask:0xf bank_mask:0xf
	v_mov_b32_dpp v205, v101 row_ror:15 row_mask:0xf bank_mask:0xf
; #define LAS __attribute__((address_space(3)))
; DEV unsigned cvt_pk_bf16(float lo, float hi) { unsigned r; asm volatile("v_cvt_pk_bf16_f32 %0, %1, %2" : "=v"(r) : "v"(lo), "v"(hi)); return r; }
; #define ROR1(x) __int_as_float(__builtin_amdgcn_update_dpp(0, __float_as_int(x), 0x121, 0xf, 0xf, false))
; #define ROR15(x) __int_as_float(__builtin_amdgcn_update_dpp(0, __float_as_int(x), 0x12F, 0xf, 0xf, false))
;     DEV void operator()(const Acc& acc, const Unit& u, int wr, int wc, int fr, int fq, LAS unsigned char* misc) const {
;     ...
;             const f32x4 w0 = *(const f32x4*)(cw + j), w1 = *(const f32x4*)(cw + DFF + j), w2 = *(const f32x4*)(cw + 2 * DFF + j), bb = *(const f32x4*)(cb + j);
; #pragma unroll
;             for (int ai = 0; ai < 2; ++ai) { const int q = 2 * ai + wr;
;                 const f32x4 bup = (q > 0) ? *(LAS f32x4*)(xl + (q - 1) * 128 + cc) : (f32x4){0.f, 0.f, 0.f, 0.f};
;                 const f32x4 bdn = (q < 3) ? *(LAS f32x4*)(xf + (q + 1) * 128 + cc) : (f32x4){0.f, 0.f, 0.f, 0.f};
;                 f32x4 Rprev = bup, Dcur;
; #pragma unroll
;                 for (int e = 0; e < 4; ++e) Dcur[e] = ROR15(acc[ai][0][0][n][e]);
; #pragma unroll
;                 for (int m = 0; m < 4; ++m) {
;                     f32x4 Rm, Dnext = bdn;
; #pragma unroll
;                     for (int e = 0; e < 4; ++e) { Rm[e] = ROR1(acc[ai][0][m][n][e]); if (m < 3) Dnext[e] = ROR15(acc[ai][0][m < 3 ? m + 1 : 3][n][e]); }
;                     const f32x4 up = (fr > 0) ? Rm : Rprev;
;                     const f32x4 dn = (fr < 15) ? Dcur : Dnext;
;                     Rprev = Rm; Dcur = Dnext;
;                     const int rr = q * 64 + m * 16 + fr, sq = s0 + rr;
;                     const f32x4 g = acc[ai][0][m][n], v = acc[ai][1][m][n];
;                     f32x4 o;
; #pragma unroll
;                     for (int e = 0; e < 4; ++e) { const float z = w0[e] * up[e] + w1[e] * g[e] + w2[e] * dn[e] + bb[e]; o[e] = z * __builtin_amdgcn_rcpf(1.f + __builtin_amdgcn_exp2f(-1.4426950408889634f * z)) * v[e]; }
;                     if (rr >= 1 && rr <= 254) { u32x2 w; w.x = cvt_pk_bf16(o[0], o[1]); w.y = cvt_pk_bf16(o[2], o[3]);
;                         *(u32x2*)(act + (size_t)(sbase + sq) * DFF + j) = w; }
	v_cndmask_b32_e64 v206, v150, v194, s[8:9]
	v_cndmask_b32_e64 v207, v151, v195, s[8:9]
	v_cndmask_b32_e64 v208, v152, v196, s[8:9]
	v_cndmask_b32_e64 v209, v153, v197, s[8:9]
	v_cndmask_b32_e64 v210, v198, v202, s[10:11]
	v_cndmask_b32_e64 v211, v199, v203, s[10:11]
	v_cndmask_b32_e64 v212, v200, v204, s[10:11]
	v_cndmask_b32_e64 v213, v201, v205, s[10:11]
	v_mul_f32_e32 v126, v110, v126
	v_mul_f32_e32 v127, v111, v127
	v_mul_f32_e32 v128, v112, v128
	v_mul_f32_e32 v129, v113, v129
	v_mul_f32_e32 v210, v114, v210
	v_mul_f32_e32 v211, v115, v211
	v_mul_f32_e32 v212, v116, v212
	v_mul_f32_e32 v213, v117, v213
	v_fmac_f32_e32 v126, v106, v206
	v_fmac_f32_e32 v127, v107, v207
	v_fmac_f32_e32 v128, v108, v208
	v_fmac_f32_e32 v129, v109, v209
	v_add_f32_e32 v126, v210, v126
	v_add_f32_e32 v127, v211, v127
	v_add_f32_e32 v128, v212, v128
	v_add_f32_e32 v129, v213, v129
	v_add_f32_e32 v126, v118, v126
	v_add_f32_e32 v127, v119, v127
	v_add_f32_e32 v128, v120, v128
	v_add_f32_e32 v129, v121, v129
	v_mul_f32_e32 v206, 0xbfb8aa3b, v126
	v_mul_f32_e32 v207, 0xbfb8aa3b, v127
	v_mul_f32_e32 v208, 0xbfb8aa3b, v128
	v_mul_f32_e32 v209, 0xbfb8aa3b, v129
	v_exp_f32_e32 v206, v206
	v_exp_f32_e32 v207, v207
	v_exp_f32_e32 v208, v208
	v_exp_f32_e32 v209, v209
	v_add_f32_e32 v206, 1.0, v206
	v_add_f32_e32 v207, 1.0, v207
	v_add_f32_e32 v208, 1.0, v208
	v_add_f32_e32 v209, 1.0, v209
	v_rcp_f32_e32 v206, v206
	v_rcp_f32_e32 v207, v207
	v_rcp_f32_e32 v208, v208
	v_rcp_f32_e32 v209, v209
	v_mul_f32_e32 v126, v126, v206
	v_mul_f32_e32 v127, v127, v207
	v_mul_f32_e32 v128, v128, v208
	v_mul_f32_e32 v129, v129, v209
	v_mul_f32_e32 v126, v122, v126
	v_mul_f32_e32 v127, v123, v127
	v_mul_f32_e32 v128, v124, v128
	v_mul_f32_e32 v129, v125, v129
	v_cvt_pk_bf16_f32 v122, v126, v127
	v_cvt_pk_bf16_f32 v123, v128, v129
	v_mov_b32_dpp v194, v98 row_ror:1 row_mask:0xf bank_mask:0xf
	v_mov_b32_dpp v195, v99 row_ror:1 row_mask:0xf bank_mask:0xf
	v_mov_b32_dpp v196, v100 row_ror:1 row_mask:0xf bank_mask:0xf
	v_mov_b32_dpp v197, v101 row_ror:1 row_mask:0xf bank_mask:0xf
	v_cndmask_b32_e64 v206, v194, v150, s[8:9]
	v_cndmask_b32_e64 v207, v195, v151, s[8:9]
	v_cndmask_b32_e64 v208, v196, v152, s[8:9]
	v_cndmask_b32_e64 v209, v197, v153, s[8:9]
	s_waitcnt lgkmcnt(0)
	v_cndmask_b32_e64 v210, v202, v146, s[10:11]
	v_cndmask_b32_e64 v211, v203, v147, s[10:11]
	v_cndmask_b32_e64 v212, v204, v148, s[10:11]
	v_cndmask_b32_e64 v213, v205, v149, s[10:11]
	v_mul_f32_e32 v98, v110, v98
	v_mul_f32_e32 v99, v111, v99
	v_mul_f32_e32 v100, v112, v100
	v_mul_f32_e32 v101, v113, v101
	v_mul_f32_e32 v210, v114, v210
	v_mul_f32_e32 v211, v115, v211
	v_mul_f32_e32 v212, v116, v212
	v_mul_f32_e32 v213, v117, v213
	v_fmac_f32_e32 v98, v106, v206
	v_fmac_f32_e32 v99, v107, v207
	v_fmac_f32_e32 v100, v108, v208
	v_fmac_f32_e32 v101, v109, v209
	v_add_f32_e32 v98, v210, v98
	v_add_f32_e32 v99, v211, v99
	v_add_f32_e32 v100, v212, v100
	v_add_f32_e32 v101, v213, v101
	v_add_f32_e32 v98, v118, v98
	v_add_f32_e32 v99, v119, v99
	v_add_f32_e32 v100, v120, v100
	v_add_f32_e32 v101, v121, v101
	v_mul_f32_e32 v206, 0xbfb8aa3b, v98
	v_mul_f32_e32 v207, 0xbfb8aa3b, v99
	v_mul_f32_e32 v208, 0xbfb8aa3b, v100
	v_mul_f32_e32 v209, 0xbfb8aa3b, v101
	v_exp_f32_e32 v206, v206
	v_exp_f32_e32 v207, v207
	v_exp_f32_e32 v208, v208
	v_exp_f32_e32 v209, v209
	v_add_f32_e32 v206, 1.0, v206
	v_add_f32_e32 v207, 1.0, v207
	v_add_f32_e32 v208, 1.0, v208
	v_add_f32_e32 v209, 1.0, v209
	v_rcp_f32_e32 v206, v206
	v_rcp_f32_e32 v207, v207
	v_rcp_f32_e32 v208, v208
	v_rcp_f32_e32 v209, v209
	v_mul_f32_e32 v98, v98, v206
	v_mul_f32_e32 v99, v99, v207
	v_mul_f32_e32 v100, v100, v208
	v_mul_f32_e32 v101, v101, v209
	v_mul_f32_e32 v98, v102, v98
	v_mul_f32_e32 v99, v103, v99
	v_mul_f32_e32 v100, v104, v100
	v_mul_f32_e32 v101, v105, v101
	v_cvt_pk_bf16_f32 v102, v98, v99
	v_cvt_pk_bf16_f32 v103, v100, v101
	global_load_dwordx4 v[138:141], v173, s[52:53] offset:16
	global_load_dwordx4 v[134:137], v173, s[20:21] offset:16
	global_load_dwordx4 v[126:129], v173, s[22:23] offset:16
	global_load_dwordx4 v[98:101], v173, s[54:55] offset:16
	ds_read_b128 v[146:149], v176 offset:1024
	v_mov_b32_dpp v198, v94 row_ror:15 row_mask:0xf bank_mask:0xf
	v_mov_b32_dpp v199, v95 row_ror:15 row_mask:0xf bank_mask:0xf
	v_mov_b32_dpp v200, v96 row_ror:15 row_mask:0xf bank_mask:0xf
	v_mov_b32_dpp v201, v97 row_ror:15 row_mask:0xf bank_mask:0xf
	v_mov_b32_dpp v150, v94 row_ror:1 row_mask:0xf bank_mask:0xf
	v_mov_b32_dpp v151, v95 row_ror:1 row_mask:0xf bank_mask:0xf
	v_mov_b32_dpp v152, v96 row_ror:1 row_mask:0xf bank_mask:0xf
	v_mov_b32_dpp v153, v97 row_ror:1 row_mask:0xf bank_mask:0xf
	v_mov_b32_dpp v202, v86 row_ror:15 row_mask:0xf bank_mask:0xf
	v_mov_b32_dpp v203, v87 row_ror:15 row_mask:0xf bank_mask:0xf
	v_mov_b32_dpp v204, v88 row_ror:15 row_mask:0xf bank_mask:0xf
	v_mov_b32_dpp v205, v89 row_ror:15 row_mask:0xf bank_mask:0xf
	s_waitcnt lgkmcnt(0)
	v_cndmask_b32_e64 v206, v150, v146, s[8:9]
	v_cndmask_b32_e64 v207, v151, v147, s[8:9]
	v_cndmask_b32_e64 v208, v152, v148, s[8:9]
	v_cndmask_b32_e64 v209, v153, v149, s[8:9]
	s_cmp_eq_u32 s7, 0
	s_cbranch_scc0 .LffnA_bz_4
	ds_read_b128 v[146:149], v176 offset:4096
	s_branch .LffnA_bj_5

; DEV unsigned cvt_pk_bf16(float lo, float hi) { unsigned r; asm volatile("v_cvt_pk_bf16_f32 %0, %1, %2" : "=v"(r) : "v"(lo), "v"(hi)); return r; }
; #define ROR1(x) __int_as_float(__builtin_amdgcn_update_dpp(0, __float_as_int(x), 0x121, 0xf, 0xf, false))
; #define ROR15(x) __int_as_float(__builtin_amdgcn_update_dpp(0, __float_as_int(x), 0x12F, 0xf, 0xf, false))
;     DEV void operator()(const Acc& acc, const Unit& u, int wr, int wc, int fr, int fq, LAS unsigned char* misc) const {
;     ...
;                 for (int m = 0; m < 4; ++m) {
;                     f32x4 Rm, Dnext = bdn;
; #pragma unroll
;                     for (int e = 0; e < 4; ++e) { Rm[e] = ROR1(acc[ai][0][m][n][e]); if (m < 3) Dnext[e] = ROR15(acc[ai][0][m < 3 ? m + 1 : 3][n][e]); }
;                     const f32x4 up = (fr > 0) ? Rm : Rprev;
;                     const f32x4 dn = (fr < 15) ? Dcur : Dnext;
;                     Rprev = Rm; Dcur = Dnext;
;                     const int rr = q * 64 + m * 16 + fr, sq = s0 + rr;
;                     const f32x4 g = acc[ai][0][m][n], v = acc[ai][1][m][n];
;                     f32x4 o;
; #pragma unroll
;                     for (int e = 0; e < 4; ++e) { const float z = w0[e] * up[e] + w1[e] * g[e] + w2[e] * dn[e] + bb[e]; o[e] = z * __builtin_amdgcn_rcpf(1.f + __builtin_amdgcn_exp2f(-1.4426950408889634f * z)) * v[e]; }
;                     if (rr >= 1 && rr <= 254) { u32x2 w; w.x = cvt_pk_bf16(o[0], o[1]); w.y = cvt_pk_bf16(o[2], o[3]);
;                         *(u32x2*)(act + (size_t)(sbase + sq) * DFF + j) = w; }
;                     if (rr < 2 || rr > 253) { const int rid = rr < 2 ? rr : rr - 252; *(f32x4*)(sbp + (size_t)rid * DFF + j) = g;
;                         if (rr == 0 || rr == 255) *(f32x4*)(sbp + (size_t)(4 + (rr == 255)) * DFF + j) = v; }
.LffnA_bj_5:
	v_cndmask_b32_e64 v210, v198, v202, s[10:11]
	v_cndmask_b32_e64 v211, v199, v203, s[10:11]
	v_cndmask_b32_e64 v212, v200, v204, s[10:11]
	v_cndmask_b32_e64 v213, v201, v205, s[10:11]
	v_mul_f32_e32 v94, v110, v94
	v_mul_f32_e32 v95, v111, v95
	v_mul_f32_e32 v96, v112, v96
	v_mul_f32_e32 v97, v113, v97
	v_mul_f32_e32 v210, v114, v210
	v_mul_f32_e32 v211, v115, v211
	v_mul_f32_e32 v212, v116, v212
	v_mul_f32_e32 v213, v117, v213
	v_fmac_f32_e32 v94, v106, v206
	v_fmac_f32_e32 v95, v107, v207
	v_fmac_f32_e32 v96, v108, v208
	v_fmac_f32_e32 v97, v109, v209
	v_add_f32_e32 v94, v210, v94
	v_add_f32_e32 v95, v211, v95
	v_add_f32_e32 v96, v212, v96
	v_add_f32_e32 v97, v213, v97
	v_add_f32_e32 v94, v118, v94
	v_add_f32_e32 v95, v119, v95
	v_add_f32_e32 v96, v120, v96
	v_add_f32_e32 v97, v121, v97
	v_mul_f32_e32 v206, 0xbfb8aa3b, v94
	v_mul_f32_e32 v207, 0xbfb8aa3b, v95
	v_mul_f32_e32 v208, 0xbfb8aa3b, v96
	v_mul_f32_e32 v209, 0xbfb8aa3b, v97
	v_exp_f32_e32 v206, v206
	v_exp_f32_e32 v207, v207
	v_exp_f32_e32 v208, v208
	v_exp_f32_e32 v209, v209
	v_add_f32_e32 v206, 1.0, v206
	v_add_f32_e32 v207, 1.0, v207
	v_add_f32_e32 v208, 1.0, v208
	v_add_f32_e32 v209, 1.0, v209
	v_rcp_f32_e32 v206, v206
	v_rcp_f32_e32 v207, v207
	v_rcp_f32_e32 v208, v208
	v_rcp_f32_e32 v209, v209
	v_mul_f32_e32 v94, v94, v206
	v_mul_f32_e32 v95, v95, v207
	v_mul_f32_e32 v96, v96, v208
	v_mul_f32_e32 v97, v97, v209
	v_mul_f32_e32 v94, v90, v94
	v_mul_f32_e32 v95, v91, v95
	v_mul_f32_e32 v96, v92, v96
	v_mul_f32_e32 v97, v93, v97
	v_cvt_pk_bf16_f32 v90, v94, v95
	v_cvt_pk_bf16_f32 v91, v96, v97
	v_mov_b32_dpp v194, v86 row_ror:1 row_mask:0xf bank_mask:0xf
	v_mov_b32_dpp v195, v87 row_ror:1 row_mask:0xf bank_mask:0xf
	v_mov_b32_dpp v196, v88 row_ror:1 row_mask:0xf bank_mask:0xf
	v_mov_b32_dpp v197, v89 row_ror:1 row_mask:0xf bank_mask:0xf
	v_mov_b32_dpp v198, v78 row_ror:15 row_mask:0xf bank_mask:0xf
	v_mov_b32_dpp v199, v79 row_ror:15 row_mask:0xf bank_mask:0xf
	v_mov_b32_dpp v200, v80 row_ror:15 row_mask:0xf bank_mask:0xf
	v_mov_b32_dpp v201, v81 row_ror:15 row_mask:0xf bank_mask:0xf
	v_cndmask_b32_e64 v206, v194, v150, s[8:9]
	v_cndmask_b32_e64 v207, v195, v151, s[8:9]
	v_cndmask_b32_e64 v208, v196, v152, s[8:9]
	v_cndmask_b32_e64 v209, v197, v153, s[8:9]
	v_cndmask_b32_e64 v210, v202, v198, s[10:11]
	v_cndmask_b32_e64 v211, v203, v199, s[10:11]
	v_cndmask_b32_e64 v212, v204, v200, s[10:11]
	v_cndmask_b32_e64 v213, v205, v201, s[10:11]
	v_mul_f32_e32 v86, v110, v86
	v_mul_f32_e32 v87, v111, v87
	v_mul_f32_e32 v88, v112, v88
	v_mul_f32_e32 v89, v113, v89
	v_mul_f32_e32 v210, v114, v210
	v_mul_f32_e32 v211, v115, v211
	v_mul_f32_e32 v212, v116, v212
	v_mul_f32_e32 v213, v117, v213
	v_fmac_f32_e32 v86, v106, v206
	v_fmac_f32_e32 v87, v107, v207
	v_fmac_f32_e32 v88, v108, v208
	v_fmac_f32_e32 v89, v109, v209
	v_add_f32_e32 v86, v210, v86
	v_add_f32_e32 v87, v211, v87
	v_add_f32_e32 v88, v212, v88
	v_add_f32_e32 v89, v213, v89
	v_add_f32_e32 v86, v118, v86
	v_add_f32_e32 v87, v119, v87
	v_add_f32_e32 v88, v120, v88
	v_add_f32_e32 v89, v121, v89
	v_mul_f32_e32 v206, 0xbfb8aa3b, v86
	v_mul_f32_e32 v207, 0xbfb8aa3b, v87
	v_mul_f32_e32 v208, 0xbfb8aa3b, v88
	v_mul_f32_e32 v209, 0xbfb8aa3b, v89
	v_exp_f32_e32 v206, v206
	v_exp_f32_e32 v207, v207
	v_exp_f32_e32 v208, v208
	v_exp_f32_e32 v209, v209
	v_add_f32_e32 v206, 1.0, v206
	v_add_f32_e32 v207, 1.0, v207
	v_add_f32_e32 v208, 1.0, v208
	v_add_f32_e32 v209, 1.0, v209
	v_rcp_f32_e32 v206, v206
	v_rcp_f32_e32 v207, v207
	v_rcp_f32_e32 v208, v208
	v_rcp_f32_e32 v209, v209
	v_mul_f32_e32 v86, v86, v206
	v_mul_f32_e32 v87, v87, v207
	v_mul_f32_e32 v88, v88, v208
	v_mul_f32_e32 v89, v89, v209
	v_mul_f32_e32 v86, v82, v86
	v_mul_f32_e32 v87, v83, v87
	v_mul_f32_e32 v88, v84, v88
	v_mul_f32_e32 v89, v85, v89
	v_cvt_pk_bf16_f32 v82, v86, v87
	v_cvt_pk_bf16_f32 v83, v88, v89
	v_mov_b32_dpp v150, v78 row_ror:1 row_mask:0xf bank_mask:0xf
	v_mov_b32_dpp v151, v79 row_ror:1 row_mask:0xf bank_mask:0xf
	v_mov_b32_dpp v152, v80 row_ror:1 row_mask:0xf bank_mask:0xf
	v_mov_b32_dpp v153, v81 row_ror:1 row_mask:0xf bank_mask:0xf
	v_mov_b32_dpp v202, v70 row_ror:15 row_mask:0xf bank_mask:0xf
	v_mov_b32_dpp v203, v71 row_ror:15 row_mask:0xf bank_mask:0xf
	v_mov_b32_dpp v204, v72 row_ror:15 row_mask:0xf bank_mask:0xf
	v_mov_b32_dpp v205, v73 row_ror:15 row_mask:0xf bank_mask:0xf
	v_cndmask_b32_e64 v206, v150, v194, s[8:9]
	v_cndmask_b32_e64 v207, v151, v195, s[8:9]
	v_cndmask_b32_e64 v208, v152, v196, s[8:9]
	v_cndmask_b32_e64 v209, v153, v197, s[8:9]
	v_cndmask_b32_e64 v210, v198, v202, s[10:11]
	v_cndmask_b32_e64 v211, v199, v203, s[10:11]
	v_cndmask_b32_e64 v212, v200, v204, s[10:11]
	v_cndmask_b32_e64 v213, v201, v205, s[10:11]
	v_mul_f32_e32 v78, v110, v78
	v_mul_f32_e32 v79, v111, v79
	v_mul_f32_e32 v80, v112, v80
	v_mul_f32_e32 v81, v113, v81
	v_mul_f32_e32 v210, v114, v210
	v_mul_f32_e32 v211, v115, v211
	v_mul_f32_e32 v212, v116, v212
	v_mul_f32_e32 v213, v117, v213
	v_fmac_f32_e32 v78, v106, v206
	v_fmac_f32_e32 v79, v107, v207
	v_fmac_f32_e32 v80, v108, v208
	v_fmac_f32_e32 v81, v109, v209
	v_add_f32_e32 v78, v210, v78
	v_add_f32_e32 v79, v211, v79
	v_add_f32_e32 v80, v212, v80
	v_add_f32_e32 v81, v213, v81
	v_add_f32_e32 v78, v118, v78
	v_add_f32_e32 v79, v119, v79
	v_add_f32_e32 v80, v120, v80
	v_add_f32_e32 v81, v121, v81
	v_mul_f32_e32 v206, 0xbfb8aa3b, v78
	v_mul_f32_e32 v207, 0xbfb8aa3b, v79
	v_mul_f32_e32 v208, 0xbfb8aa3b, v80
	v_mul_f32_e32 v209, 0xbfb8aa3b, v81
	v_exp_f32_e32 v206, v206
	v_exp_f32_e32 v207, v207
	v_exp_f32_e32 v208, v208
	v_exp_f32_e32 v209, v209
	v_add_f32_e32 v206, 1.0, v206
	v_add_f32_e32 v207, 1.0, v207
	v_add_f32_e32 v208, 1.0, v208
	v_add_f32_e32 v209, 1.0, v209
	v_rcp_f32_e32 v206, v206
	v_rcp_f32_e32 v207, v207
	v_rcp_f32_e32 v208, v208
	v_rcp_f32_e32 v209, v209
	v_mul_f32_e32 v78, v78, v206
	v_mul_f32_e32 v79, v79, v207
	v_mul_f32_e32 v80, v80, v208
	v_mul_f32_e32 v81, v81, v209
	v_mul_f32_e32 v78, v74, v78
	v_mul_f32_e32 v79, v75, v79
	v_mul_f32_e32 v80, v76, v80
	v_mul_f32_e32 v81, v77, v81
	v_cvt_pk_bf16_f32 v74, v78, v79
	v_cvt_pk_bf16_f32 v75, v80, v81
	s_cmp_eq_u32 s7, 1
	s_cbranch_scc0 .LffnA_ns_6
	v_mul_u32_u24_e32 v177, 0x2c00, v172
	v_cmp_lt_u32_e64 s[30:31], 13, v172
	v_add_u32_e32 v177, v177, v173
	v_add_u32_e32 v177, 0xfffdf000, v177
	s_nop 1
	s_mov_b64 exec, s[30:31]
	global_store_dwordx4 v177, v[70:73], s[24:25]
	s_mov_b64 exec, s[10:11]
	global_store_dwordx4 v177, v[66:69], s[28:29]
	s_mov_b64 exec, -1
	s_nop 4
; DEV unsigned cvt_pk_bf16(float lo, float hi) { unsigned r; asm volatile("v_cvt_pk_bf16_f32 %0, %1, %2" : "=v"(r) : "v"(lo), "v"(hi)); return r; }
; #define ROR1(x) __int_as_float(__builtin_amdgcn_update_dpp(0, __float_as_int(x), 0x121, 0xf, 0xf, false))
; #define ROR15(x) __int_as_float(__builtin_amdgcn_update_dpp(0, __float_as_int(x), 0x12F, 0xf, 0xf, false))
;     DEV void operator()(const Acc& acc, const Unit& u, int wr, int wc, int fr, int fq, LAS unsigned char* misc) const {
;     ...
;                 for (int m = 0; m < 4; ++m) {
;                     f32x4 Rm, Dnext = bdn;
; #pragma unroll
;                     for (int e = 0; e < 4; ++e) { Rm[e] = ROR1(acc[ai][0][m][n][e]); if (m < 3) Dnext[e] = ROR15(acc[ai][0][m < 3 ? m + 1 : 3][n][e]); }
;                     const f32x4 up = (fr > 0) ? Rm : Rprev;
;                     const f32x4 dn = (fr < 15) ? Dcur : Dnext;
;                     Rprev = Rm; Dcur = Dnext;
;                     const int rr = q * 64 + m * 16 + fr, sq = s0 + rr;
;                     const f32x4 g = acc[ai][0][m][n], v = acc[ai][1][m][n];
;                     f32x4 o;
; #pragma unroll
;                     for (int e = 0; e < 4; ++e) { const float z = w0[e] * up[e] + w1[e] * g[e] + w2[e] * dn[e] + bb[e]; o[e] = z * __builtin_amdgcn_rcpf(1.f + __builtin_amdgcn_exp2f(-1.4426950408889634f * z)) * v[e]; }
;                     if (rr >= 1 && rr <= 254) { u32x2 w; w.x = cvt_pk_bf16(o[0], o[1]); w.y = cvt_pk_bf16(o[2], o[3]);
;                         *(u32x2*)(act + (size_t)(sbase + sq) * DFF + j) = w; }
.LffnA_ns_6:
	v_mov_b32_dpp v194, v70 row_ror:1 row_mask:0xf bank_mask:0xf
	v_mov_b32_dpp v195, v71 row_ror:1 row_mask:0xf bank_mask:0xf
	v_mov_b32_dpp v196, v72 row_ror:1 row_mask:0xf bank_mask:0xf
	v_mov_b32_dpp v197, v73 row_ror:1 row_mask:0xf bank_mask:0xf
	v_cndmask_b32_e64 v206, v194, v150, s[8:9]
	v_cndmask_b32_e64 v207, v195, v151, s[8:9]
	v_cndmask_b32_e64 v208, v196, v152, s[8:9]
	v_cndmask_b32_e64 v209, v197, v153, s[8:9]
	s_waitcnt lgkmcnt(0)
	v_cndmask_b32_e64 v210, v202, v146, s[10:11]
	v_cndmask_b32_e64 v211, v203, v147, s[10:11]
	v_cndmask_b32_e64 v212, v204, v148, s[10:11]
	v_cndmask_b32_e64 v213, v205, v149, s[10:11]
	v_mul_f32_e32 v70, v110, v70
	v_mul_f32_e32 v71, v111, v71
	v_mul_f32_e32 v72, v112, v72
	v_mul_f32_e32 v73, v113, v73
	v_mul_f32_e32 v210, v114, v210
	v_mul_f32_e32 v211, v115, v211
	v_mul_f32_e32 v212, v116, v212
	v_mul_f32_e32 v213, v117, v213
	v_fmac_f32_e32 v70, v106, v206
	v_fmac_f32_e32 v71, v107, v207
	v_fmac_f32_e32 v72, v108, v208
	v_fmac_f32_e32 v73, v109, v209
	v_add_f32_e32 v70, v210, v70
	v_add_f32_e32 v71, v211, v71
	v_add_f32_e32 v72, v212, v72
	v_add_f32_e32 v73, v213, v73
	v_add_f32_e32 v70, v118, v70
	v_add_f32_e32 v71, v119, v71
	v_add_f32_e32 v72, v120, v72
	v_add_f32_e32 v73, v121, v73
	v_mul_f32_e32 v206, 0xbfb8aa3b, v70
	v_mul_f32_e32 v207, 0xbfb8aa3b, v71
	v_mul_f32_e32 v208, 0xbfb8aa3b, v72
	v_mul_f32_e32 v209, 0xbfb8aa3b, v73
	v_exp_f32_e32 v206, v206
	v_exp_f32_e32 v207, v207
	v_exp_f32_e32 v208, v208
	v_exp_f32_e32 v209, v209
	v_add_f32_e32 v206, 1.0, v206
	v_add_f32_e32 v207, 1.0, v207
	v_add_f32_e32 v208, 1.0, v208
	v_add_f32_e32 v209, 1.0, v209
	v_rcp_f32_e32 v206, v206
	v_rcp_f32_e32 v207, v207
	v_rcp_f32_e32 v208, v208
	v_rcp_f32_e32 v209, v209
	v_mul_f32_e32 v70, v70, v206
	v_mul_f32_e32 v71, v71, v207
	v_mul_f32_e32 v72, v72, v208
	v_mul_f32_e32 v73, v73, v209
	v_mul_f32_e32 v70, v66, v70
	v_mul_f32_e32 v71, v67, v71
	v_mul_f32_e32 v72, v68, v72
	v_mul_f32_e32 v73, v69, v73
	v_cvt_pk_bf16_f32 v66, v70, v71
	v_cvt_pk_bf16_f32 v67, v72, v73
	s_cmp_eq_u32 s7, 0
	s_cbranch_scc1 .LffnA_bz_7
	ds_read_b128 v[146:149], v176 offset:16
	s_branch .LffnA_bj_8

; #define LAS __attribute__((address_space(3)))
; DEV unsigned cvt_pk_bf16(float lo, float hi) { unsigned r; asm volatile("v_cvt_pk_bf16_f32 %0, %1, %2" : "=v"(r) : "v"(lo), "v"(hi)); return r; }
;     DEV void operator()(const Acc& acc, const Unit& u, int wr, int wc, int fr, int fq, LAS unsigned char* misc) const {
;     ...
;         for (int n = 0; n < 2; ++n) { const int cc = wc * 32 + 8 * fq + 4 * n, j = u.pn * 128 + cc;
;             const f32x4 w0 = *(const f32x4*)(cw + j), w1 = *(const f32x4*)(cw + DFF + j), w2 = *(const f32x4*)(cw + 2 * DFF + j), bb = *(const f32x4*)(cb + j);
; #pragma unroll
;             for (int ai = 0; ai < 2; ++ai) { const int q = 2 * ai + wr;
;                 const f32x4 bup = (q > 0) ? *(LAS f32x4*)(xl + (q - 1) * 128 + cc) : (f32x4){0.f, 0.f, 0.f, 0.f};
;                 const f32x4 bdn = (q < 3) ? *(LAS f32x4*)(xf + (q + 1) * 128 + cc) : (f32x4){0.f, 0.f, 0.f, 0.f};
;                 f32x4 Rprev = bup, Dcur;
; #pragma unroll
;                 for (int e = 0; e < 4; ++e) Dcur[e] = ROR15(acc[ai][0][0][n][e]);
; #pragma unroll
;                 for (int m = 0; m < 4; ++m) {
;                     f32x4 Rm, Dnext = bdn;
; #pragma unroll
;                     for (int e = 0; e < 4; ++e) { Rm[e] = ROR1(acc[ai][0][m][n][e]); if (m < 3) Dnext[e] = ROR15(acc[ai][0][m < 3 ? m + 1 : 3][n][e]); }
;                     const f32x4 up = (fr > 0) ? Rm : Rprev;
;                     const f32x4 dn = (fr < 15) ? Dcur : Dnext;
;                     Rprev = Rm; Dcur = Dnext;
;                     const int rr = q * 64 + m * 16 + fr, sq = s0 + rr;
;                     const f32x4 g = acc[ai][0][m][n], v = acc[ai][1][m][n];
;                     f32x4 o;
; #pragma unroll
;                     for (int e = 0; e < 4; ++e) { const float z = w0[e] * up[e] + w1[e] * g[e] + w2[e] * dn[e] + bb[e]; o[e] = z * __builtin_amdgcn_rcpf(1.f + __builtin_amdgcn_exp2f(-1.4426950408889634f * z)) * v[e]; }
;                     if (rr >= 1 && rr <= 254) { u32x2 w; w.x = cvt_pk_bf16(o[0], o[1]); w.y = cvt_pk_bf16(o[2], o[3]);
;                         *(u32x2*)(act + (size_t)(sbase + sq) * DFF + j) = w; }
;                     if (rr < 2 || rr > 253) { const int rid = rr < 2 ? rr : rr - 252; *(f32x4*)(sbp + (size_t)rid * DFF + j) = g;
;                         if (rr == 0 || rr == 255) *(f32x4*)(sbp + (size_t)(4 + (rr == 255)) * DFF + j) = v; }
.LffnA_bj_8:
	v_mov_b32_dpp v198, v58 row_ror:15 row_mask:0xf bank_mask:0xf
	v_mov_b32_dpp v199, v59 row_ror:15 row_mask:0xf bank_mask:0xf
	v_mov_b32_dpp v200, v60 row_ror:15 row_mask:0xf bank_mask:0xf
	v_mov_b32_dpp v201, v61 row_ror:15 row_mask:0xf bank_mask:0xf
	s_waitcnt vmcnt(0)
	s_cmp_eq_u32 s7, 0
	s_cbranch_scc0 .LffnA_ns_9
	v_mul_u32_u24_e32 v177, 0x2c00, v172
	v_cmp_gt_u32_e64 s[30:31], 2, v172
	v_add_u32_e32 v177, v177, v173
	s_nop 1
	s_mov_b64 exec, s[30:31]
	global_store_dwordx4 v177, v[58:61], s[24:25] offset:16
	s_mov_b64 exec, s[8:9]
	global_store_dwordx4 v177, v[62:65], s[26:27] offset:16
	s_mov_b64 exec, -1
	s_nop 4
.LffnA_ns_9:
	v_mov_b32_dpp v150, v58 row_ror:1 row_mask:0xf bank_mask:0xf
	v_mov_b32_dpp v151, v59 row_ror:1 row_mask:0xf bank_mask:0xf
	v_mov_b32_dpp v152, v60 row_ror:1 row_mask:0xf bank_mask:0xf
	v_mov_b32_dpp v153, v61 row_ror:1 row_mask:0xf bank_mask:0xf
	v_mov_b32_dpp v202, v54 row_ror:15 row_mask:0xf bank_mask:0xf
	v_mov_b32_dpp v203, v55 row_ror:15 row_mask:0xf bank_mask:0xf
	v_mov_b32_dpp v204, v56 row_ror:15 row_mask:0xf bank_mask:0xf
	v_mov_b32_dpp v205, v57 row_ror:15 row_mask:0xf bank_mask:0xf
	s_waitcnt lgkmcnt(0)
	v_cndmask_b32_e64 v206, v150, v146, s[8:9]
	v_cndmask_b32_e64 v207, v151, v147, s[8:9]
	v_cndmask_b32_e64 v208, v152, v148, s[8:9]
	v_cndmask_b32_e64 v209, v153, v149, s[8:9]
	ds_read_b128 v[146:149], v176 offset:3088
	v_cndmask_b32_e64 v210, v198, v202, s[10:11]
	v_cndmask_b32_e64 v211, v199, v203, s[10:11]
	v_cndmask_b32_e64 v212, v200, v204, s[10:11]
	v_cndmask_b32_e64 v213, v201, v205, s[10:11]
	v_mul_f32_e32 v58, v134, v58
	v_mul_f32_e32 v59, v135, v59
	v_mul_f32_e32 v60, v136, v60
	v_mul_f32_e32 v61, v137, v61
	v_mul_f32_e32 v210, v126, v210
	v_mul_f32_e32 v211, v127, v211
	v_mul_f32_e32 v212, v128, v212
	v_mul_f32_e32 v213, v129, v213
	v_fmac_f32_e32 v58, v138, v206
	v_fmac_f32_e32 v59, v139, v207
	v_fmac_f32_e32 v60, v140, v208
	v_fmac_f32_e32 v61, v141, v209
	v_add_f32_e32 v58, v210, v58
	v_add_f32_e32 v59, v211, v59
	v_add_f32_e32 v60, v212, v60
	v_add_f32_e32 v61, v213, v61
	v_add_f32_e32 v58, v98, v58
	v_add_f32_e32 v59, v99, v59
	v_add_f32_e32 v60, v100, v60
	v_add_f32_e32 v61, v101, v61
	v_mul_f32_e32 v206, 0xbfb8aa3b, v58
	v_mul_f32_e32 v207, 0xbfb8aa3b, v59
	v_mul_f32_e32 v208, 0xbfb8aa3b, v60
	v_mul_f32_e32 v209, 0xbfb8aa3b, v61
	v_exp_f32_e32 v206, v206
	v_exp_f32_e32 v207, v207
	v_exp_f32_e32 v208, v208
	v_exp_f32_e32 v209, v209
	v_add_f32_e32 v206, 1.0, v206
	v_add_f32_e32 v207, 1.0, v207
	v_add_f32_e32 v208, 1.0, v208
	v_add_f32_e32 v209, 1.0, v209
	v_rcp_f32_e32 v206, v206
	v_rcp_f32_e32 v207, v207
	v_rcp_f32_e32 v208, v208
	v_rcp_f32_e32 v209, v209
	v_mul_f32_e32 v58, v58, v206
	v_mul_f32_e32 v59, v59, v207
	v_mul_f32_e32 v60, v60, v208
	v_mul_f32_e32 v61, v61, v209
	v_mul_f32_e32 v58, v62, v58
	v_mul_f32_e32 v59, v63, v59
	v_mul_f32_e32 v60, v64, v60
	v_mul_f32_e32 v61, v65, v61
	v_cvt_pk_bf16_f32 v144, v58, v59
	v_cvt_pk_bf16_f32 v145, v60, v61
	v_add_u32_e32 v175, 0x0, v174
	s_mov_b64 exec, s[12:13]
	global_store_dwordx4 v175, v[142:145], s[18:19]
	s_mov_b64 exec, -1
	s_nop 4
	v_mov_b32_dpp v194, v54 row_ror:1 row_mask:0xf bank_mask:0xf
	v_mov_b32_dpp v195, v55 row_ror:1 row_mask:0xf bank_mask:0xf
	v_mov_b32_dpp v196, v56 row_ror:1 row_mask:0xf bank_mask:0xf
	v_mov_b32_dpp v197, v57 row_ror:1 row_mask:0xf bank_mask:0xf
	v_mov_b32_dpp v198, v46 row_ror:15 row_mask:0xf bank_mask:0xf
	v_mov_b32_dpp v199, v47 row_ror:15 row_mask:0xf bank_mask:0xf
	v_mov_b32_dpp v200, v48 row_ror:15 row_mask:0xf bank_mask:0xf
	v_mov_b32_dpp v201, v49 row_ror:15 row_mask:0xf bank_mask:0xf
	v_cndmask_b32_e64 v206, v194, v150, s[8:9]
	v_cndmask_b32_e64 v207, v195, v151, s[8:9]
	v_cndmask_b32_e64 v208, v196, v152, s[8:9]
	v_cndmask_b32_e64 v209, v197, v153, s[8:9]
	v_cndmask_b32_e64 v210, v202, v198, s[10:11]
	v_cndmask_b32_e64 v211, v203, v199, s[10:11]
	v_cndmask_b32_e64 v212, v204, v200, s[10:11]
	v_cndmask_b32_e64 v213, v205, v201, s[10:11]
	v_mul_f32_e32 v54, v134, v54
	v_mul_f32_e32 v55, v135, v55
	v_mul_f32_e32 v56, v136, v56
	v_mul_f32_e32 v57, v137, v57
	v_mul_f32_e32 v210, v126, v210
	v_mul_f32_e32 v211, v127, v211
	v_mul_f32_e32 v212, v128, v212
	v_mul_f32_e32 v213, v129, v213
	v_fmac_f32_e32 v54, v138, v206
	v_fmac_f32_e32 v55, v139, v207
	v_fmac_f32_e32 v56, v140, v208
	v_fmac_f32_e32 v57, v141, v209
	v_add_f32_e32 v54, v210, v54
	v_add_f32_e32 v55, v211, v55
	v_add_f32_e32 v56, v212, v56
	v_add_f32_e32 v57, v213, v57
	v_add_f32_e32 v54, v98, v54
	v_add_f32_e32 v55, v99, v55
	v_add_f32_e32 v56, v100, v56
	v_add_f32_e32 v57, v101, v57
	v_mul_f32_e32 v206, 0xbfb8aa3b, v54
	v_mul_f32_e32 v207, 0xbfb8aa3b, v55
	v_mul_f32_e32 v208, 0xbfb8aa3b, v56
	v_mul_f32_e32 v209, 0xbfb8aa3b, v57
	v_exp_f32_e32 v206, v206
	v_exp_f32_e32 v207, v207
	v_exp_f32_e32 v208, v208
	v_exp_f32_e32 v209, v209
	v_add_f32_e32 v206, 1.0, v206
	v_add_f32_e32 v207, 1.0, v207
	v_add_f32_e32 v208, 1.0, v208
	v_add_f32_e32 v209, 1.0, v209
	v_rcp_f32_e32 v206, v206
	v_rcp_f32_e32 v207, v207
	v_rcp_f32_e32 v208, v208
	v_rcp_f32_e32 v209, v209
	v_mul_f32_e32 v54, v54, v206
	v_mul_f32_e32 v55, v55, v207
	v_mul_f32_e32 v56, v56, v208
	v_mul_f32_e32 v57, v57, v209
	v_mul_f32_e32 v54, v50, v54
	v_mul_f32_e32 v55, v51, v55
	v_mul_f32_e32 v56, v52, v56
	v_mul_f32_e32 v57, v53, v57
	v_cvt_pk_bf16_f32 v132, v54, v55
	v_cvt_pk_bf16_f32 v133, v56, v57
	v_add_u32_e32 v175, 0x16000, v174
	global_store_dwordx4 v175, v[130:133], s[18:19]
	v_mov_b32_dpp v150, v46 row_ror:1 row_mask:0xf bank_mask:0xf
; DEV unsigned cvt_pk_bf16(float lo, float hi) { unsigned r; asm volatile("v_cvt_pk_bf16_f32 %0, %1, %2" : "=v"(r) : "v"(lo), "v"(hi)); return r; }
; #define ROR1(x) __int_as_float(__builtin_amdgcn_update_dpp(0, __float_as_int(x), 0x121, 0xf, 0xf, false))
; #define ROR15(x) __int_as_float(__builtin_amdgcn_update_dpp(0, __float_as_int(x), 0x12F, 0xf, 0xf, false))
;     DEV void operator()(const Acc& acc, const Unit& u, int wr, int wc, int fr, int fq, LAS unsigned char* misc) const {
;     ...
;                 for (int m = 0; m < 4; ++m) {
;                     f32x4 Rm, Dnext = bdn;
; #pragma unroll
;                     for (int e = 0; e < 4; ++e) { Rm[e] = ROR1(acc[ai][0][m][n][e]); if (m < 3) Dnext[e] = ROR15(acc[ai][0][m < 3 ? m + 1 : 3][n][e]); }
;                     const f32x4 up = (fr > 0) ? Rm : Rprev;
;                     const f32x4 dn = (fr < 15) ? Dcur : Dnext;
;                     Rprev = Rm; Dcur = Dnext;
;                     const int rr = q * 64 + m * 16 + fr, sq = s0 + rr;
;                     const f32x4 g = acc[ai][0][m][n], v = acc[ai][1][m][n];
;                     f32x4 o;
; #pragma unroll
;                     for (int e = 0; e < 4; ++e) { const float z = w0[e] * up[e] + w1[e] * g[e] + w2[e] * dn[e] + bb[e]; o[e] = z * __builtin_amdgcn_rcpf(1.f + __builtin_amdgcn_exp2f(-1.4426950408889634f * z)) * v[e]; }
;                     if (rr >= 1 && rr <= 254) { u32x2 w; w.x = cvt_pk_bf16(o[0], o[1]); w.y = cvt_pk_bf16(o[2], o[3]);
;                         *(u32x2*)(act + (size_t)(sbase + sq) * DFF + j) = w; }
	v_mov_b32_dpp v151, v47 row_ror:1 row_mask:0xf bank_mask:0xf
	v_mov_b32_dpp v152, v48 row_ror:1 row_mask:0xf bank_mask:0xf
	v_mov_b32_dpp v153, v49 row_ror:1 row_mask:0xf bank_mask:0xf
	v_mov_b32_dpp v202, v34 row_ror:15 row_mask:0xf bank_mask:0xf
	v_mov_b32_dpp v203, v35 row_ror:15 row_mask:0xf bank_mask:0xf
	v_mov_b32_dpp v204, v36 row_ror:15 row_mask:0xf bank_mask:0xf
	v_mov_b32_dpp v205, v37 row_ror:15 row_mask:0xf bank_mask:0xf
	v_cndmask_b32_e64 v206, v150, v194, s[8:9]
	v_cndmask_b32_e64 v207, v151, v195, s[8:9]
	v_cndmask_b32_e64 v208, v152, v196, s[8:9]
	v_cndmask_b32_e64 v209, v153, v197, s[8:9]
	v_cndmask_b32_e64 v210, v198, v202, s[10:11]
	v_cndmask_b32_e64 v211, v199, v203, s[10:11]
	v_cndmask_b32_e64 v212, v200, v204, s[10:11]
	v_cndmask_b32_e64 v213, v201, v205, s[10:11]
	v_mul_f32_e32 v46, v134, v46
	v_mul_f32_e32 v47, v135, v47
	v_mul_f32_e32 v48, v136, v48
	v_mul_f32_e32 v49, v137, v49
	v_mul_f32_e32 v210, v126, v210
	v_mul_f32_e32 v211, v127, v211
	v_mul_f32_e32 v212, v128, v212
	v_mul_f32_e32 v213, v129, v213
	v_fmac_f32_e32 v46, v138, v206
	v_fmac_f32_e32 v47, v139, v207
	v_fmac_f32_e32 v48, v140, v208
	v_fmac_f32_e32 v49, v141, v209
	v_add_f32_e32 v46, v210, v46
	v_add_f32_e32 v47, v211, v47
	v_add_f32_e32 v48, v212, v48
	v_add_f32_e32 v49, v213, v49
	v_add_f32_e32 v46, v98, v46
	v_add_f32_e32 v47, v99, v47
	v_add_f32_e32 v48, v100, v48
	v_add_f32_e32 v49, v101, v49
	v_mul_f32_e32 v206, 0xbfb8aa3b, v46
	v_mul_f32_e32 v207, 0xbfb8aa3b, v47
	v_mul_f32_e32 v208, 0xbfb8aa3b, v48
	v_mul_f32_e32 v209, 0xbfb8aa3b, v49
	v_exp_f32_e32 v206, v206
	v_exp_f32_e32 v207, v207
	v_exp_f32_e32 v208, v208
	v_exp_f32_e32 v209, v209
	v_add_f32_e32 v206, 1.0, v206
	v_add_f32_e32 v207, 1.0, v207
	v_add_f32_e32 v208, 1.0, v208
	v_add_f32_e32 v209, 1.0, v209
	v_rcp_f32_e32 v206, v206
	v_rcp_f32_e32 v207, v207
	v_rcp_f32_e32 v208, v208
	v_rcp_f32_e32 v209, v209
	v_mul_f32_e32 v46, v46, v206
	v_mul_f32_e32 v47, v47, v207
	v_mul_f32_e32 v48, v48, v208
	v_mul_f32_e32 v49, v49, v209
	v_mul_f32_e32 v46, v42, v46
	v_mul_f32_e32 v47, v43, v47
	v_mul_f32_e32 v48, v44, v48
	v_mul_f32_e32 v49, v45, v49
	v_cvt_pk_bf16_f32 v124, v46, v47
	v_cvt_pk_bf16_f32 v125, v48, v49
	v_add_u32_e32 v175, 0x2c000, v174
	global_store_dwordx4 v175, v[122:125], s[18:19]
	v_mov_b32_dpp v194, v34 row_ror:1 row_mask:0xf bank_mask:0xf
	v_mov_b32_dpp v195, v35 row_ror:1 row_mask:0xf bank_mask:0xf
	v_mov_b32_dpp v196, v36 row_ror:1 row_mask:0xf bank_mask:0xf
	v_mov_b32_dpp v197, v37 row_ror:1 row_mask:0xf bank_mask:0xf
	v_cndmask_b32_e64 v206, v194, v150, s[8:9]
	v_cndmask_b32_e64 v207, v195, v151, s[8:9]
	v_cndmask_b32_e64 v208, v196, v152, s[8:9]
	v_cndmask_b32_e64 v209, v197, v153, s[8:9]
	s_waitcnt lgkmcnt(0)
	v_cndmask_b32_e64 v210, v202, v146, s[10:11]
	v_cndmask_b32_e64 v211, v203, v147, s[10:11]
	v_cndmask_b32_e64 v212, v204, v148, s[10:11]
	v_cndmask_b32_e64 v213, v205, v149, s[10:11]
	v_mul_f32_e32 v34, v134, v34
	v_mul_f32_e32 v35, v135, v35
	v_mul_f32_e32 v36, v136, v36
	v_mul_f32_e32 v37, v137, v37
	v_mul_f32_e32 v210, v126, v210
	v_mul_f32_e32 v211, v127, v211
	v_mul_f32_e32 v212, v128, v212
	v_mul_f32_e32 v213, v129, v213
	v_fmac_f32_e32 v34, v138, v206
	v_fmac_f32_e32 v35, v139, v207
	v_fmac_f32_e32 v36, v140, v208
	v_fmac_f32_e32 v37, v141, v209
	v_add_f32_e32 v34, v210, v34
	v_add_f32_e32 v35, v211, v35
	v_add_f32_e32 v36, v212, v36
	v_add_f32_e32 v37, v213, v37
	v_add_f32_e32 v34, v98, v34
	v_add_f32_e32 v35, v99, v35
	v_add_f32_e32 v36, v100, v36
	v_add_f32_e32 v37, v101, v37
	v_mul_f32_e32 v206, 0xbfb8aa3b, v34
	v_mul_f32_e32 v207, 0xbfb8aa3b, v35
	v_mul_f32_e32 v208, 0xbfb8aa3b, v36
	v_mul_f32_e32 v209, 0xbfb8aa3b, v37
	v_exp_f32_e32 v206, v206
	v_exp_f32_e32 v207, v207
	v_exp_f32_e32 v208, v208
	v_exp_f32_e32 v209, v209
	v_add_f32_e32 v206, 1.0, v206
	v_add_f32_e32 v207, 1.0, v207
	v_add_f32_e32 v208, 1.0, v208
	v_add_f32_e32 v209, 1.0, v209
	v_rcp_f32_e32 v206, v206
	v_rcp_f32_e32 v207, v207
	v_rcp_f32_e32 v208, v208
	v_rcp_f32_e32 v209, v209
	v_mul_f32_e32 v34, v34, v206
	v_mul_f32_e32 v35, v35, v207
	v_mul_f32_e32 v36, v36, v208
	v_mul_f32_e32 v37, v37, v209
	v_mul_f32_e32 v34, v38, v34
	v_mul_f32_e32 v35, v39, v35
	v_mul_f32_e32 v36, v40, v36
	v_mul_f32_e32 v37, v41, v37
	v_cvt_pk_bf16_f32 v104, v34, v35
	v_cvt_pk_bf16_f32 v105, v36, v37
	v_add_u32_e32 v175, 0x42000, v174
	global_store_dwordx4 v175, v[102:105], s[18:19]
	ds_read_b128 v[146:149], v176 offset:1040
	v_mov_b32_dpp v198, v30 row_ror:15 row_mask:0xf bank_mask:0xf
	v_mov_b32_dpp v199, v31 row_ror:15 row_mask:0xf bank_mask:0xf
	v_mov_b32_dpp v200, v32 row_ror:15 row_mask:0xf bank_mask:0xf
	v_mov_b32_dpp v201, v33 row_ror:15 row_mask:0xf bank_mask:0xf
	v_mov_b32_dpp v150, v30 row_ror:1 row_mask:0xf bank_mask:0xf
	v_mov_b32_dpp v151, v31 row_ror:1 row_mask:0xf bank_mask:0xf
	v_mov_b32_dpp v152, v32 row_ror:1 row_mask:0xf bank_mask:0xf
	v_mov_b32_dpp v153, v33 row_ror:1 row_mask:0xf bank_mask:0xf
	v_mov_b32_dpp v202, v22 row_ror:15 row_mask:0xf bank_mask:0xf
	v_mov_b32_dpp v203, v23 row_ror:15 row_mask:0xf bank_mask:0xf
	v_mov_b32_dpp v204, v24 row_ror:15 row_mask:0xf bank_mask:0xf
	v_mov_b32_dpp v205, v25 row_ror:15 row_mask:0xf bank_mask:0xf
	s_waitcnt lgkmcnt(0)
	v_cndmask_b32_e64 v206, v150, v146, s[8:9]
	v_cndmask_b32_e64 v207, v151, v147, s[8:9]
	v_cndmask_b32_e64 v208, v152, v148, s[8:9]
	v_cndmask_b32_e64 v209, v153, v149, s[8:9]
	s_cmp_eq_u32 s7, 0
	s_cbranch_scc0 .LffnA_bz_10
	ds_read_b128 v[146:149], v176 offset:4112
	s_branch .LffnA_bj_11

; DEV unsigned cvt_pk_bf16(float lo, float hi) { unsigned r; asm volatile("v_cvt_pk_bf16_f32 %0, %1, %2" : "=v"(r) : "v"(lo), "v"(hi)); return r; }
; #define ROR1(x) __int_as_float(__builtin_amdgcn_update_dpp(0, __float_as_int(x), 0x121, 0xf, 0xf, false))
; #define ROR15(x) __int_as_float(__builtin_amdgcn_update_dpp(0, __float_as_int(x), 0x12F, 0xf, 0xf, false))
;     DEV void operator()(const Acc& acc, const Unit& u, int wr, int wc, int fr, int fq, LAS unsigned char* misc) const {
;     ...
;                 for (int m = 0; m < 4; ++m) {
;                     f32x4 Rm, Dnext = bdn;
; #pragma unroll
;                     for (int e = 0; e < 4; ++e) { Rm[e] = ROR1(acc[ai][0][m][n][e]); if (m < 3) Dnext[e] = ROR15(acc[ai][0][m < 3 ? m + 1 : 3][n][e]); }
;                     const f32x4 up = (fr > 0) ? Rm : Rprev;
;                     const f32x4 dn = (fr < 15) ? Dcur : Dnext;
;                     Rprev = Rm; Dcur = Dnext;
;                     const int rr = q * 64 + m * 16 + fr, sq = s0 + rr;
;                     const f32x4 g = acc[ai][0][m][n], v = acc[ai][1][m][n];
;                     f32x4 o;
; #pragma unroll
;                     for (int e = 0; e < 4; ++e) { const float z = w0[e] * up[e] + w1[e] * g[e] + w2[e] * dn[e] + bb[e]; o[e] = z * __builtin_amdgcn_rcpf(1.f + __builtin_amdgcn_exp2f(-1.4426950408889634f * z)) * v[e]; }
;                     if (rr >= 1 && rr <= 254) { u32x2 w; w.x = cvt_pk_bf16(o[0], o[1]); w.y = cvt_pk_bf16(o[2], o[3]);
;                         *(u32x2*)(act + (size_t)(sbase + sq) * DFF + j) = w; }
;                     if (rr < 2 || rr > 253) { const int rid = rr < 2 ? rr : rr - 252; *(f32x4*)(sbp + (size_t)rid * DFF + j) = g;
;                         if (rr == 0 || rr == 255) *(f32x4*)(sbp + (size_t)(4 + (rr == 255)) * DFF + j) = v; }
.LffnA_bj_11:
	v_cndmask_b32_e64 v210, v198, v202, s[10:11]
	v_cndmask_b32_e64 v211, v199, v203, s[10:11]
	v_cndmask_b32_e64 v212, v200, v204, s[10:11]
	v_cndmask_b32_e64 v213, v201, v205, s[10:11]
	v_mul_f32_e32 v30, v134, v30
	v_mul_f32_e32 v31, v135, v31
	v_mul_f32_e32 v32, v136, v32
	v_mul_f32_e32 v33, v137, v33
	v_mul_f32_e32 v210, v126, v210
	v_mul_f32_e32 v211, v127, v211
	v_mul_f32_e32 v212, v128, v212
	v_mul_f32_e32 v213, v129, v213
	v_fmac_f32_e32 v30, v138, v206
	v_fmac_f32_e32 v31, v139, v207
	v_fmac_f32_e32 v32, v140, v208
	v_fmac_f32_e32 v33, v141, v209
	v_add_f32_e32 v30, v210, v30
	v_add_f32_e32 v31, v211, v31
	v_add_f32_e32 v32, v212, v32
	v_add_f32_e32 v33, v213, v33
	v_add_f32_e32 v30, v98, v30
	v_add_f32_e32 v31, v99, v31
	v_add_f32_e32 v32, v100, v32
	v_add_f32_e32 v33, v101, v33
	v_mul_f32_e32 v206, 0xbfb8aa3b, v30
	v_mul_f32_e32 v207, 0xbfb8aa3b, v31
	v_mul_f32_e32 v208, 0xbfb8aa3b, v32
	v_mul_f32_e32 v209, 0xbfb8aa3b, v33
	v_exp_f32_e32 v206, v206
	v_exp_f32_e32 v207, v207
	v_exp_f32_e32 v208, v208
	v_exp_f32_e32 v209, v209
	v_add_f32_e32 v206, 1.0, v206
	v_add_f32_e32 v207, 1.0, v207
	v_add_f32_e32 v208, 1.0, v208
	v_add_f32_e32 v209, 1.0, v209
	v_rcp_f32_e32 v206, v206
	v_rcp_f32_e32 v207, v207
	v_rcp_f32_e32 v208, v208
	v_rcp_f32_e32 v209, v209
	v_mul_f32_e32 v30, v30, v206
	v_mul_f32_e32 v31, v31, v207
	v_mul_f32_e32 v32, v32, v208
	v_mul_f32_e32 v33, v33, v209
	v_mul_f32_e32 v30, v26, v30
	v_mul_f32_e32 v31, v27, v31
	v_mul_f32_e32 v32, v28, v32
	v_mul_f32_e32 v33, v29, v33
	v_cvt_pk_bf16_f32 v92, v30, v31
	v_cvt_pk_bf16_f32 v93, v32, v33
	v_add_u32_e32 v175, 0xb0000, v174
	global_store_dwordx4 v175, v[90:93], s[18:19]
	v_mov_b32_dpp v194, v22 row_ror:1 row_mask:0xf bank_mask:0xf
	v_mov_b32_dpp v195, v23 row_ror:1 row_mask:0xf bank_mask:0xf
	v_mov_b32_dpp v196, v24 row_ror:1 row_mask:0xf bank_mask:0xf
	v_mov_b32_dpp v197, v25 row_ror:1 row_mask:0xf bank_mask:0xf
	v_mov_b32_dpp v198, v14 row_ror:15 row_mask:0xf bank_mask:0xf
	v_mov_b32_dpp v199, v15 row_ror:15 row_mask:0xf bank_mask:0xf
	v_mov_b32_dpp v200, v16 row_ror:15 row_mask:0xf bank_mask:0xf
	v_mov_b32_dpp v201, v17 row_ror:15 row_mask:0xf bank_mask:0xf
	v_cndmask_b32_e64 v206, v194, v150, s[8:9]
	v_cndmask_b32_e64 v207, v195, v151, s[8:9]
	v_cndmask_b32_e64 v208, v196, v152, s[8:9]
	v_cndmask_b32_e64 v209, v197, v153, s[8:9]
	v_cndmask_b32_e64 v210, v202, v198, s[10:11]
	v_cndmask_b32_e64 v211, v203, v199, s[10:11]
	v_cndmask_b32_e64 v212, v204, v200, s[10:11]
	v_cndmask_b32_e64 v213, v205, v201, s[10:11]
	v_mul_f32_e32 v22, v134, v22
	v_mul_f32_e32 v23, v135, v23
	v_mul_f32_e32 v24, v136, v24
	v_mul_f32_e32 v25, v137, v25
	v_mul_f32_e32 v210, v126, v210
	v_mul_f32_e32 v211, v127, v211
	v_mul_f32_e32 v212, v128, v212
	v_mul_f32_e32 v213, v129, v213
	v_fmac_f32_e32 v22, v138, v206
	v_fmac_f32_e32 v23, v139, v207
	v_fmac_f32_e32 v24, v140, v208
	v_fmac_f32_e32 v25, v141, v209
	v_add_f32_e32 v22, v210, v22
	v_add_f32_e32 v23, v211, v23
	v_add_f32_e32 v24, v212, v24
	v_add_f32_e32 v25, v213, v25
	v_add_f32_e32 v22, v98, v22
	v_add_f32_e32 v23, v99, v23
	v_add_f32_e32 v24, v100, v24
	v_add_f32_e32 v25, v101, v25
	v_mul_f32_e32 v206, 0xbfb8aa3b, v22
	v_mul_f32_e32 v207, 0xbfb8aa3b, v23
	v_mul_f32_e32 v208, 0xbfb8aa3b, v24
	v_mul_f32_e32 v209, 0xbfb8aa3b, v25
	v_exp_f32_e32 v206, v206
	v_exp_f32_e32 v207, v207
	v_exp_f32_e32 v208, v208
	v_exp_f32_e32 v209, v209
	v_add_f32_e32 v206, 1.0, v206
	v_add_f32_e32 v207, 1.0, v207
	v_add_f32_e32 v208, 1.0, v208
	v_add_f32_e32 v209, 1.0, v209
	v_rcp_f32_e32 v206, v206
	v_rcp_f32_e32 v207, v207
	v_rcp_f32_e32 v208, v208
	v_rcp_f32_e32 v209, v209
	v_mul_f32_e32 v22, v22, v206
	v_mul_f32_e32 v23, v23, v207
	v_mul_f32_e32 v24, v24, v208
	v_mul_f32_e32 v25, v25, v209
	v_mul_f32_e32 v22, v18, v22
	v_mul_f32_e32 v23, v19, v23
	v_mul_f32_e32 v24, v20, v24
	v_mul_f32_e32 v25, v21, v25
	v_cvt_pk_bf16_f32 v84, v22, v23
	v_cvt_pk_bf16_f32 v85, v24, v25
	v_add_u32_e32 v175, 0xc6000, v174
	global_store_dwordx4 v175, v[82:85], s[18:19]
	v_mov_b32_dpp v150, v14 row_ror:1 row_mask:0xf bank_mask:0xf
	v_mov_b32_dpp v151, v15 row_ror:1 row_mask:0xf bank_mask:0xf
	v_mov_b32_dpp v152, v16 row_ror:1 row_mask:0xf bank_mask:0xf
	v_mov_b32_dpp v153, v17 row_ror:1 row_mask:0xf bank_mask:0xf
	v_mov_b32_dpp v202, v6 row_ror:15 row_mask:0xf bank_mask:0xf
	v_mov_b32_dpp v203, v7 row_ror:15 row_mask:0xf bank_mask:0xf
	v_mov_b32_dpp v204, v8 row_ror:15 row_mask:0xf bank_mask:0xf
	v_mov_b32_dpp v205, v9 row_ror:15 row_mask:0xf bank_mask:0xf
	v_cndmask_b32_e64 v206, v150, v194, s[8:9]
	v_cndmask_b32_e64 v207, v151, v195, s[8:9]
	v_cndmask_b32_e64 v208, v152, v196, s[8:9]
	v_cndmask_b32_e64 v209, v153, v197, s[8:9]
	v_cndmask_b32_e64 v210, v198, v202, s[10:11]
	v_cndmask_b32_e64 v211, v199, v203, s[10:11]
	v_cndmask_b32_e64 v212, v200, v204, s[10:11]
	v_cndmask_b32_e64 v213, v201, v205, s[10:11]
	v_mul_f32_e32 v14, v134, v14
	v_mul_f32_e32 v15, v135, v15
	v_mul_f32_e32 v16, v136, v16
	v_mul_f32_e32 v17, v137, v17
	v_mul_f32_e32 v210, v126, v210
	v_mul_f32_e32 v211, v127, v211
	v_mul_f32_e32 v212, v128, v212
	v_mul_f32_e32 v213, v129, v213
	v_fmac_f32_e32 v14, v138, v206
	v_fmac_f32_e32 v15, v139, v207
	v_fmac_f32_e32 v16, v140, v208
	v_fmac_f32_e32 v17, v141, v209
	v_add_f32_e32 v14, v210, v14
	v_add_f32_e32 v15, v211, v15
	v_add_f32_e32 v16, v212, v16
	v_add_f32_e32 v17, v213, v17
	v_add_f32_e32 v14, v98, v14
	v_add_f32_e32 v15, v99, v15
	v_add_f32_e32 v16, v100, v16
	v_add_f32_e32 v17, v101, v17
	v_mul_f32_e32 v206, 0xbfb8aa3b, v14
	v_mul_f32_e32 v207, 0xbfb8aa3b, v15
	v_mul_f32_e32 v208, 0xbfb8aa3b, v16
	v_mul_f32_e32 v209, 0xbfb8aa3b, v17
	v_exp_f32_e32 v206, v206
	v_exp_f32_e32 v207, v207
	v_exp_f32_e32 v208, v208
	v_exp_f32_e32 v209, v209
	v_add_f32_e32 v206, 1.0, v206
	v_add_f32_e32 v207, 1.0, v207
	v_add_f32_e32 v208, 1.0, v208
	v_add_f32_e32 v209, 1.0, v209
	v_rcp_f32_e32 v206, v206
	v_rcp_f32_e32 v207, v207
	v_rcp_f32_e32 v208, v208
	v_rcp_f32_e32 v209, v209
	v_mul_f32_e32 v14, v14, v206
	v_mul_f32_e32 v15, v15, v207
	v_mul_f32_e32 v16, v16, v208
	v_mul_f32_e32 v17, v17, v209
	v_mul_f32_e32 v14, v10, v14
	v_mul_f32_e32 v15, v11, v15
	v_mul_f32_e32 v16, v12, v16
	v_mul_f32_e32 v17, v13, v17
	v_cvt_pk_bf16_f32 v76, v14, v15
	v_cvt_pk_bf16_f32 v77, v16, v17
	v_add_u32_e32 v175, 0xdc000, v174
	global_store_dwordx4 v175, v[74:77], s[18:19]
	s_cmp_eq_u32 s7, 1
	s_cbranch_scc0 .LffnA_ns_12
	v_mul_u32_u24_e32 v177, 0x2c00, v172
	v_cmp_lt_u32_e64 s[30:31], 13, v172
	v_add_u32_e32 v177, v177, v173
	v_add_u32_e32 v177, 0xfffdf000, v177
	s_nop 1
	s_mov_b64 exec, s[30:31]
	global_store_dwordx4 v177, v[6:9], s[24:25] offset:16
	s_mov_b64 exec, s[10:11]
	global_store_dwordx4 v177, v[2:5], s[28:29] offset:16
	s_mov_b64 exec, -1
	s_nop 4
; DEV unsigned cvt_pk_bf16(float lo, float hi) { unsigned r; asm volatile("v_cvt_pk_bf16_f32 %0, %1, %2" : "=v"(r) : "v"(lo), "v"(hi)); return r; }
; #define ROR1(x) __int_as_float(__builtin_amdgcn_update_dpp(0, __float_as_int(x), 0x121, 0xf, 0xf, false))
; #define ROR15(x) __int_as_float(__builtin_amdgcn_update_dpp(0, __float_as_int(x), 0x12F, 0xf, 0xf, false))
;     DEV void operator()(const Acc& acc, const Unit& u, int wr, int wc, int fr, int fq, LAS unsigned char* misc) const {
;     ...
;                 for (int m = 0; m < 4; ++m) {
;                     f32x4 Rm, Dnext = bdn;
; #pragma unroll
;                     for (int e = 0; e < 4; ++e) { Rm[e] = ROR1(acc[ai][0][m][n][e]); if (m < 3) Dnext[e] = ROR15(acc[ai][0][m < 3 ? m + 1 : 3][n][e]); }
;                     const f32x4 up = (fr > 0) ? Rm : Rprev;
;                     const f32x4 dn = (fr < 15) ? Dcur : Dnext;
;                     Rprev = Rm; Dcur = Dnext;
;                     const int rr = q * 64 + m * 16 + fr, sq = s0 + rr;
;                     const f32x4 g = acc[ai][0][m][n], v = acc[ai][1][m][n];
;                     f32x4 o;
; #pragma unroll
;                     for (int e = 0; e < 4; ++e) { const float z = w0[e] * up[e] + w1[e] * g[e] + w2[e] * dn[e] + bb[e]; o[e] = z * __builtin_amdgcn_rcpf(1.f + __builtin_amdgcn_exp2f(-1.4426950408889634f * z)) * v[e]; }
;                     if (rr >= 1 && rr <= 254) { u32x2 w; w.x = cvt_pk_bf16(o[0], o[1]); w.y = cvt_pk_bf16(o[2], o[3]);
;                         *(u32x2*)(act + (size_t)(sbase + sq) * DFF + j) = w; }
;                     if (rr < 2 || rr > 253) { const int rid = rr < 2 ? rr : rr - 252; *(f32x4*)(sbp + (size_t)rid * DFF + j) = g;
;                         if (rr == 0 || rr == 255) *(f32x4*)(sbp + (size_t)(4 + (rr == 255)) * DFF + j) = v; }
;                 }
;                 asm volatile("" ::: "memory");
;             } }
.LffnA_ns_12:
	v_mov_b32_dpp v194, v6 row_ror:1 row_mask:0xf bank_mask:0xf
	v_mov_b32_dpp v195, v7 row_ror:1 row_mask:0xf bank_mask:0xf
	v_mov_b32_dpp v196, v8 row_ror:1 row_mask:0xf bank_mask:0xf
	v_mov_b32_dpp v197, v9 row_ror:1 row_mask:0xf bank_mask:0xf
	v_cndmask_b32_e64 v206, v194, v150, s[8:9]
	v_cndmask_b32_e64 v207, v195, v151, s[8:9]
	v_cndmask_b32_e64 v208, v196, v152, s[8:9]
	v_cndmask_b32_e64 v209, v197, v153, s[8:9]
	s_waitcnt lgkmcnt(0)
	v_cndmask_b32_e64 v210, v202, v146, s[10:11]
	v_cndmask_b32_e64 v211, v203, v147, s[10:11]
	v_cndmask_b32_e64 v212, v204, v148, s[10:11]
	v_cndmask_b32_e64 v213, v205, v149, s[10:11]
	v_mul_f32_e32 v6, v134, v6
	v_mul_f32_e32 v7, v135, v7
	v_mul_f32_e32 v8, v136, v8
	v_mul_f32_e32 v9, v137, v9
	v_mul_f32_e32 v210, v126, v210
	v_mul_f32_e32 v211, v127, v211
	v_mul_f32_e32 v212, v128, v212
	v_mul_f32_e32 v213, v129, v213
	v_fmac_f32_e32 v6, v138, v206
	v_fmac_f32_e32 v7, v139, v207
	v_fmac_f32_e32 v8, v140, v208
	v_fmac_f32_e32 v9, v141, v209
	v_add_f32_e32 v6, v210, v6
	v_add_f32_e32 v7, v211, v7
	v_add_f32_e32 v8, v212, v8
	v_add_f32_e32 v9, v213, v9
	v_add_f32_e32 v6, v98, v6
	v_add_f32_e32 v7, v99, v7
	v_add_f32_e32 v8, v100, v8
	v_add_f32_e32 v9, v101, v9
	v_mul_f32_e32 v206, 0xbfb8aa3b, v6
	v_mul_f32_e32 v207, 0xbfb8aa3b, v7
	v_mul_f32_e32 v208, 0xbfb8aa3b, v8
	v_mul_f32_e32 v209, 0xbfb8aa3b, v9
	v_exp_f32_e32 v206, v206
	v_exp_f32_e32 v207, v207
	v_exp_f32_e32 v208, v208
	v_exp_f32_e32 v209, v209
	v_add_f32_e32 v206, 1.0, v206
	v_add_f32_e32 v207, 1.0, v207
	v_add_f32_e32 v208, 1.0, v208
	v_add_f32_e32 v209, 1.0, v209
	v_rcp_f32_e32 v206, v206
	v_rcp_f32_e32 v207, v207
	v_rcp_f32_e32 v208, v208
	v_rcp_f32_e32 v209, v209
	v_mul_f32_e32 v6, v6, v206
	v_mul_f32_e32 v7, v7, v207
	v_mul_f32_e32 v8, v8, v208
	v_mul_f32_e32 v9, v9, v209
	v_mul_f32_e32 v6, v2, v6
	v_mul_f32_e32 v7, v3, v7
	v_mul_f32_e32 v8, v4, v8
	v_mul_f32_e32 v9, v5, v9
	v_cvt_pk_bf16_f32 v68, v6, v7
	v_cvt_pk_bf16_f32 v69, v8, v9
	v_add_u32_e32 v175, 0xf2000, v174
	s_mov_b64 exec, s[16:17]
	global_store_dwordx4 v175, v[66:69], s[18:19]
	s_mov_b64 exec, -1
	s_nop 4
	s_and_b64 vcc, exec, s[2:3]
	s_mov_b64 s[2:3], -1
	s_cbranch_vccnz .LBB0_284
	v_readlane_b32 s2, v249, 51
	v_readlane_b32 s3, v249, 52
	s_andn2_b64 vcc, exec, s[2:3]
	s_cbranch_vccnz .LBB0_283
	s_barrier
	s_branch .LBB0_283

; DEV void grid_barrier(unsigned* cnt, const unsigned target, const int tid) {
;     asm volatile("s_waitcnt vmcnt(0)" ::: "memory");
;     __syncthreads();
;     if (tid == 0) {
;         __builtin_amdgcn_fence(__ATOMIC_RELEASE, "agent");
;         __hip_atomic_fetch_add(cnt, 1u, __ATOMIC_RELAXED, __HIP_MEMORY_SCOPE_AGENT);
;         while (__hip_atomic_load(cnt, __ATOMIC_RELAXED, __HIP_MEMORY_SCOPE_AGENT) < target) __builtin_amdgcn_s_sleep(28);
;         __builtin_amdgcn_fence(__ATOMIC_ACQUIRE, "agent");
;         asm volatile("s_waitcnt vmcnt(0)" ::: "memory");
;     }
;     __syncthreads();
; }
.Lgb2_follow:
.Lgb2_poll:
	global_load_dword v4, v2, s[2:3] offset:64 sc1
	s_waitcnt vmcnt(0)
	v_cmp_gt_u32_e32 vcc, s5, v4
	s_cbranch_vccz .Lgb2_done
	s_sleep 8
	s_branch .Lgb2_poll

; DEV unsigned cvt_pk_bf16(float lo, float hi) { unsigned r; asm volatile("v_cvt_pk_bf16_f32 %0, %1, %2" : "=v"(r) : "v"(lo), "v"(hi)); return r; }
; #define ROR1(x) __int_as_float(__builtin_amdgcn_update_dpp(0, __float_as_int(x), 0x121, 0xf, 0xf, false))
; #define ROR15(x) __int_as_float(__builtin_amdgcn_update_dpp(0, __float_as_int(x), 0x12F, 0xf, 0xf, false))
;     DEV void operator()(const Acc& acc, const Unit& u, int wr, int wc, int fr, int fq, LAS unsigned char* misc) const {
;     ...
;                 for (int m = 0; m < 4; ++m) {
;                     f32x4 Rm, Dnext = bdn;
; #pragma unroll
;                     for (int e = 0; e < 4; ++e) { Rm[e] = ROR1(acc[ai][0][m][n][e]); if (m < 3) Dnext[e] = ROR15(acc[ai][0][m < 3 ? m + 1 : 3][n][e]); }
;                     const f32x4 up = (fr > 0) ? Rm : Rprev;
;                     const f32x4 dn = (fr < 15) ? Dcur : Dnext;
;                     Rprev = Rm; Dcur = Dnext;
;                     const int rr = q * 64 + m * 16 + fr, sq = s0 + rr;
;                     const f32x4 g = acc[ai][0][m][n], v = acc[ai][1][m][n];
;                     f32x4 o;
; #pragma unroll
;                     for (int e = 0; e < 4; ++e) { const float z = w0[e] * up[e] + w1[e] * g[e] + w2[e] * dn[e] + bb[e]; o[e] = z * __builtin_amdgcn_rcpf(1.f + __builtin_amdgcn_exp2f(-1.4426950408889634f * z)) * v[e]; }
;                     if (rr >= 1 && rr <= 254) { u32x2 w; w.x = cvt_pk_bf16(o[0], o[1]); w.y = cvt_pk_bf16(o[2], o[3]);
;                         *(u32x2*)(act + (size_t)(sbase + sq) * DFF + j) = w; }
.LffnB_ns_3:
	v_mov_b32_dpp v150, v138 row_ror:1 row_mask:0xf bank_mask:0xf
	v_mov_b32_dpp v151, v139 row_ror:1 row_mask:0xf bank_mask:0xf
	v_mov_b32_dpp v152, v140 row_ror:1 row_mask:0xf bank_mask:0xf
	v_mov_b32_dpp v153, v141 row_ror:1 row_mask:0xf bank_mask:0xf
	v_mov_b32_dpp v198, v134 row_ror:15 row_mask:0xf bank_mask:0xf
	v_mov_b32_dpp v199, v135 row_ror:15 row_mask:0xf bank_mask:0xf
	v_mov_b32_dpp v200, v136 row_ror:15 row_mask:0xf bank_mask:0xf
	v_mov_b32_dpp v201, v137 row_ror:15 row_mask:0xf bank_mask:0xf
	s_waitcnt lgkmcnt(0)
	v_cndmask_b32_e64 v202, v150, v146, s[8:9]
	v_cndmask_b32_e64 v203, v151, v147, s[8:9]
	v_cndmask_b32_e64 v204, v152, v148, s[8:9]
	v_cndmask_b32_e64 v205, v153, v149, s[8:9]
	ds_read_b128 v[146:149], v170 offset:3072
	v_cndmask_b32_e64 v206, v194, v198, s[10:11]
	v_cndmask_b32_e64 v207, v195, v199, s[10:11]
	v_cndmask_b32_e64 v208, v196, v200, s[10:11]
	v_cndmask_b32_e64 v209, v197, v201, s[10:11]
	v_mul_f32_e32 v138, v110, v138
	v_mul_f32_e32 v139, v111, v139
	v_mul_f32_e32 v140, v112, v140
	v_mul_f32_e32 v141, v113, v141
	v_mul_f32_e32 v206, v114, v206
	v_mul_f32_e32 v207, v115, v207
	v_mul_f32_e32 v208, v116, v208
	v_mul_f32_e32 v209, v117, v209
	v_fmac_f32_e32 v138, v106, v202
	v_fmac_f32_e32 v139, v107, v203
	v_fmac_f32_e32 v140, v108, v204
	v_fmac_f32_e32 v141, v109, v205
	v_add_f32_e32 v138, v206, v138
	v_add_f32_e32 v139, v207, v139
	v_add_f32_e32 v140, v208, v140
	v_add_f32_e32 v141, v209, v141
	v_add_f32_e32 v138, v118, v138
	v_add_f32_e32 v139, v119, v139
	v_add_f32_e32 v140, v120, v140
	v_add_f32_e32 v141, v121, v141
	v_mul_f32_e32 v202, 0xbfb8aa3b, v138
	v_mul_f32_e32 v203, 0xbfb8aa3b, v139
	v_mul_f32_e32 v204, 0xbfb8aa3b, v140
	v_mul_f32_e32 v205, 0xbfb8aa3b, v141
	v_exp_f32_e32 v202, v202
	v_exp_f32_e32 v203, v203
	v_exp_f32_e32 v204, v204
	v_exp_f32_e32 v205, v205
	v_add_f32_e32 v202, 1.0, v202
	v_add_f32_e32 v203, 1.0, v203
	v_add_f32_e32 v204, 1.0, v204
	v_add_f32_e32 v205, 1.0, v205
	v_rcp_f32_e32 v202, v202
	v_rcp_f32_e32 v203, v203
	v_rcp_f32_e32 v204, v204
	v_rcp_f32_e32 v205, v205
	v_mul_f32_e32 v138, v138, v202
	v_mul_f32_e32 v139, v139, v203
	v_mul_f32_e32 v140, v140, v204
	v_mul_f32_e32 v141, v141, v205
	v_mul_f32_e32 v138, v142, v138
	v_mul_f32_e32 v139, v143, v139
	v_mul_f32_e32 v140, v144, v140
	v_mul_f32_e32 v141, v145, v141
	v_cvt_pk_bf16_f32 v142, v138, v139
	v_cvt_pk_bf16_f32 v143, v140, v141
	v_mov_b32_dpp v190, v134 row_ror:1 row_mask:0xf bank_mask:0xf
	v_mov_b32_dpp v191, v135 row_ror:1 row_mask:0xf bank_mask:0xf
	v_mov_b32_dpp v192, v136 row_ror:1 row_mask:0xf bank_mask:0xf
	v_mov_b32_dpp v193, v137 row_ror:1 row_mask:0xf bank_mask:0xf
	v_mov_b32_dpp v194, v126 row_ror:15 row_mask:0xf bank_mask:0xf
	v_mov_b32_dpp v195, v127 row_ror:15 row_mask:0xf bank_mask:0xf
	v_mov_b32_dpp v196, v128 row_ror:15 row_mask:0xf bank_mask:0xf
	v_mov_b32_dpp v197, v129 row_ror:15 row_mask:0xf bank_mask:0xf
	v_cndmask_b32_e64 v202, v190, v150, s[8:9]
	v_cndmask_b32_e64 v203, v191, v151, s[8:9]
	v_cndmask_b32_e64 v204, v192, v152, s[8:9]
	v_cndmask_b32_e64 v205, v193, v153, s[8:9]
	v_cndmask_b32_e64 v206, v198, v194, s[10:11]
	v_cndmask_b32_e64 v207, v199, v195, s[10:11]
	v_cndmask_b32_e64 v208, v200, v196, s[10:11]
	v_cndmask_b32_e64 v209, v201, v197, s[10:11]
	v_mul_f32_e32 v134, v110, v134
	v_mul_f32_e32 v135, v111, v135
	v_mul_f32_e32 v136, v112, v136
	v_mul_f32_e32 v137, v113, v137
	v_mul_f32_e32 v206, v114, v206
	v_mul_f32_e32 v207, v115, v207
	v_mul_f32_e32 v208, v116, v208
	v_mul_f32_e32 v209, v117, v209
	v_fmac_f32_e32 v134, v106, v202
	v_fmac_f32_e32 v135, v107, v203
	v_fmac_f32_e32 v136, v108, v204
	v_fmac_f32_e32 v137, v109, v205
	v_add_f32_e32 v134, v206, v134
	v_add_f32_e32 v135, v207, v135
	v_add_f32_e32 v136, v208, v136
	v_add_f32_e32 v137, v209, v137
	v_add_f32_e32 v134, v118, v134
	v_add_f32_e32 v135, v119, v135
	v_add_f32_e32 v136, v120, v136
	v_add_f32_e32 v137, v121, v137
	v_mul_f32_e32 v202, 0xbfb8aa3b, v134
	v_mul_f32_e32 v203, 0xbfb8aa3b, v135
	v_mul_f32_e32 v204, 0xbfb8aa3b, v136
	v_mul_f32_e32 v205, 0xbfb8aa3b, v137
	v_exp_f32_e32 v202, v202
	v_exp_f32_e32 v203, v203
	v_exp_f32_e32 v204, v204
	v_exp_f32_e32 v205, v205
	v_add_f32_e32 v202, 1.0, v202
	v_add_f32_e32 v203, 1.0, v203
	v_add_f32_e32 v204, 1.0, v204
	v_add_f32_e32 v205, 1.0, v205
	v_rcp_f32_e32 v202, v202
	v_rcp_f32_e32 v203, v203
	v_rcp_f32_e32 v204, v204
	v_rcp_f32_e32 v205, v205
	v_mul_f32_e32 v134, v134, v202
	v_mul_f32_e32 v135, v135, v203
	v_mul_f32_e32 v136, v136, v204
	v_mul_f32_e32 v137, v137, v205
	v_mul_f32_e32 v134, v130, v134
	v_mul_f32_e32 v135, v131, v135
	v_mul_f32_e32 v136, v132, v136
	v_mul_f32_e32 v137, v133, v137
	v_cvt_pk_bf16_f32 v130, v134, v135
	v_cvt_pk_bf16_f32 v131, v136, v137
	v_mov_b32_dpp v150, v126 row_ror:1 row_mask:0xf bank_mask:0xf
	v_mov_b32_dpp v151, v127 row_ror:1 row_mask:0xf bank_mask:0xf
	v_mov_b32_dpp v152, v128 row_ror:1 row_mask:0xf bank_mask:0xf
	v_mov_b32_dpp v153, v129 row_ror:1 row_mask:0xf bank_mask:0xf
	v_mov_b32_dpp v198, v98 row_ror:15 row_mask:0xf bank_mask:0xf
	v_mov_b32_dpp v199, v99 row_ror:15 row_mask:0xf bank_mask:0xf
	v_mov_b32_dpp v200, v100 row_ror:15 row_mask:0xf bank_mask:0xf
	v_mov_b32_dpp v201, v101 row_ror:15 row_mask:0xf bank_mask:0xf
; #define LAS __attribute__((address_space(3)))
; DEV unsigned cvt_pk_bf16(float lo, float hi) { unsigned r; asm volatile("v_cvt_pk_bf16_f32 %0, %1, %2" : "=v"(r) : "v"(lo), "v"(hi)); return r; }
; #define ROR1(x) __int_as_float(__builtin_amdgcn_update_dpp(0, __float_as_int(x), 0x121, 0xf, 0xf, false))
; #define ROR15(x) __int_as_float(__builtin_amdgcn_update_dpp(0, __float_as_int(x), 0x12F, 0xf, 0xf, false))
;     DEV void operator()(const Acc& acc, const Unit& u, int wr, int wc, int fr, int fq, LAS unsigned char* misc) const {
;     ...
;             const f32x4 w0 = *(const f32x4*)(cw + j), w1 = *(const f32x4*)(cw + DFF + j), w2 = *(const f32x4*)(cw + 2 * DFF + j), bb = *(const f32x4*)(cb + j);
; #pragma unroll
;             for (int ai = 0; ai < 2; ++ai) { const int q = 2 * ai + wr;
;                 const f32x4 bup = (q > 0) ? *(LAS f32x4*)(xl + (q - 1) * 128 + cc) : (f32x4){0.f, 0.f, 0.f, 0.f};
;                 const f32x4 bdn = (q < 3) ? *(LAS f32x4*)(xf + (q + 1) * 128 + cc) : (f32x4){0.f, 0.f, 0.f, 0.f};
;                 f32x4 Rprev = bup, Dcur;
; #pragma unroll
;                 for (int e = 0; e < 4; ++e) Dcur[e] = ROR15(acc[ai][0][0][n][e]);
; #pragma unroll
;                 for (int m = 0; m < 4; ++m) {
;                     f32x4 Rm, Dnext = bdn;
; #pragma unroll
;                     for (int e = 0; e < 4; ++e) { Rm[e] = ROR1(acc[ai][0][m][n][e]); if (m < 3) Dnext[e] = ROR15(acc[ai][0][m < 3 ? m + 1 : 3][n][e]); }
;                     const f32x4 up = (fr > 0) ? Rm : Rprev;
;                     const f32x4 dn = (fr < 15) ? Dcur : Dnext;
;                     Rprev = Rm; Dcur = Dnext;
;                     const int rr = q * 64 + m * 16 + fr, sq = s0 + rr;
;                     const f32x4 g = acc[ai][0][m][n], v = acc[ai][1][m][n];
;                     f32x4 o;
; #pragma unroll
;                     for (int e = 0; e < 4; ++e) { const float z = w0[e] * up[e] + w1[e] * g[e] + w2[e] * dn[e] + bb[e]; o[e] = z * __builtin_amdgcn_rcpf(1.f + __builtin_amdgcn_exp2f(-1.4426950408889634f * z)) * v[e]; }
;                     if (rr >= 1 && rr <= 254) { u32x2 w; w.x = cvt_pk_bf16(o[0], o[1]); w.y = cvt_pk_bf16(o[2], o[3]);
;                         *(u32x2*)(act + (size_t)(sbase + sq) * DFF + j) = w; }
	v_cndmask_b32_e64 v202, v150, v190, s[8:9]
	v_cndmask_b32_e64 v203, v151, v191, s[8:9]
	v_cndmask_b32_e64 v204, v152, v192, s[8:9]
	v_cndmask_b32_e64 v205, v153, v193, s[8:9]
	v_cndmask_b32_e64 v206, v194, v198, s[10:11]
	v_cndmask_b32_e64 v207, v195, v199, s[10:11]
	v_cndmask_b32_e64 v208, v196, v200, s[10:11]
	v_cndmask_b32_e64 v209, v197, v201, s[10:11]
	v_mul_f32_e32 v126, v110, v126
	v_mul_f32_e32 v127, v111, v127
	v_mul_f32_e32 v128, v112, v128
	v_mul_f32_e32 v129, v113, v129
	v_mul_f32_e32 v206, v114, v206
	v_mul_f32_e32 v207, v115, v207
	v_mul_f32_e32 v208, v116, v208
	v_mul_f32_e32 v209, v117, v209
	v_fmac_f32_e32 v126, v106, v202
	v_fmac_f32_e32 v127, v107, v203
	v_fmac_f32_e32 v128, v108, v204
	v_fmac_f32_e32 v129, v109, v205
	v_add_f32_e32 v126, v206, v126
	v_add_f32_e32 v127, v207, v127
	v_add_f32_e32 v128, v208, v128
	v_add_f32_e32 v129, v209, v129
	v_add_f32_e32 v126, v118, v126
	v_add_f32_e32 v127, v119, v127
	v_add_f32_e32 v128, v120, v128
	v_add_f32_e32 v129, v121, v129
	v_mul_f32_e32 v202, 0xbfb8aa3b, v126
	v_mul_f32_e32 v203, 0xbfb8aa3b, v127
	v_mul_f32_e32 v204, 0xbfb8aa3b, v128
	v_mul_f32_e32 v205, 0xbfb8aa3b, v129
	v_exp_f32_e32 v202, v202
	v_exp_f32_e32 v203, v203
	v_exp_f32_e32 v204, v204
	v_exp_f32_e32 v205, v205
	v_add_f32_e32 v202, 1.0, v202
	v_add_f32_e32 v203, 1.0, v203
	v_add_f32_e32 v204, 1.0, v204
	v_add_f32_e32 v205, 1.0, v205
	v_rcp_f32_e32 v202, v202
	v_rcp_f32_e32 v203, v203
	v_rcp_f32_e32 v204, v204
	v_rcp_f32_e32 v205, v205
	v_mul_f32_e32 v126, v126, v202
	v_mul_f32_e32 v127, v127, v203
	v_mul_f32_e32 v128, v128, v204
	v_mul_f32_e32 v129, v129, v205
	v_mul_f32_e32 v126, v122, v126
	v_mul_f32_e32 v127, v123, v127
	v_mul_f32_e32 v128, v124, v128
	v_mul_f32_e32 v129, v125, v129
	v_cvt_pk_bf16_f32 v122, v126, v127
	v_cvt_pk_bf16_f32 v123, v128, v129
	v_mov_b32_dpp v190, v98 row_ror:1 row_mask:0xf bank_mask:0xf
	v_mov_b32_dpp v191, v99 row_ror:1 row_mask:0xf bank_mask:0xf
	v_mov_b32_dpp v192, v100 row_ror:1 row_mask:0xf bank_mask:0xf
	v_mov_b32_dpp v193, v101 row_ror:1 row_mask:0xf bank_mask:0xf
	v_cndmask_b32_e64 v202, v190, v150, s[8:9]
	v_cndmask_b32_e64 v203, v191, v151, s[8:9]
	v_cndmask_b32_e64 v204, v192, v152, s[8:9]
	v_cndmask_b32_e64 v205, v193, v153, s[8:9]
	s_waitcnt lgkmcnt(0)
	v_cndmask_b32_e64 v206, v198, v146, s[10:11]
	v_cndmask_b32_e64 v207, v199, v147, s[10:11]
	v_cndmask_b32_e64 v208, v200, v148, s[10:11]
	v_cndmask_b32_e64 v209, v201, v149, s[10:11]
	v_mul_f32_e32 v98, v110, v98
	v_mul_f32_e32 v99, v111, v99
	v_mul_f32_e32 v100, v112, v100
	v_mul_f32_e32 v101, v113, v101
	v_mul_f32_e32 v206, v114, v206
	v_mul_f32_e32 v207, v115, v207
	v_mul_f32_e32 v208, v116, v208
	v_mul_f32_e32 v209, v117, v209
	v_fmac_f32_e32 v98, v106, v202
	v_fmac_f32_e32 v99, v107, v203
	v_fmac_f32_e32 v100, v108, v204
	v_fmac_f32_e32 v101, v109, v205
	v_add_f32_e32 v98, v206, v98
	v_add_f32_e32 v99, v207, v99
	v_add_f32_e32 v100, v208, v100
	v_add_f32_e32 v101, v209, v101
	v_add_f32_e32 v98, v118, v98
	v_add_f32_e32 v99, v119, v99
	v_add_f32_e32 v100, v120, v100
	v_add_f32_e32 v101, v121, v101
	v_mul_f32_e32 v202, 0xbfb8aa3b, v98
	v_mul_f32_e32 v203, 0xbfb8aa3b, v99
	v_mul_f32_e32 v204, 0xbfb8aa3b, v100
	v_mul_f32_e32 v205, 0xbfb8aa3b, v101
	v_exp_f32_e32 v202, v202
	v_exp_f32_e32 v203, v203
	v_exp_f32_e32 v204, v204
	v_exp_f32_e32 v205, v205
	v_add_f32_e32 v202, 1.0, v202
	v_add_f32_e32 v203, 1.0, v203
	v_add_f32_e32 v204, 1.0, v204
	v_add_f32_e32 v205, 1.0, v205
	v_rcp_f32_e32 v202, v202
	v_rcp_f32_e32 v203, v203
	v_rcp_f32_e32 v204, v204
	v_rcp_f32_e32 v205, v205
	v_mul_f32_e32 v98, v98, v202
	v_mul_f32_e32 v99, v99, v203
	v_mul_f32_e32 v100, v100, v204
	v_mul_f32_e32 v101, v101, v205
	v_mul_f32_e32 v98, v102, v98
	v_mul_f32_e32 v99, v103, v99
	v_mul_f32_e32 v100, v104, v100
	v_mul_f32_e32 v101, v105, v101
	v_cvt_pk_bf16_f32 v102, v98, v99
	v_cvt_pk_bf16_f32 v103, v100, v101
	global_load_dwordx4 v[138:141], v167, s[54:55] offset:16
	global_load_dwordx4 v[134:137], v167, s[20:21] offset:16
	global_load_dwordx4 v[126:129], v167, s[22:23] offset:16
	global_load_dwordx4 v[98:101], v167, s[50:51] offset:16
	ds_read_b128 v[146:149], v170 offset:1024
	v_mov_b32_dpp v194, v92 row_ror:15 row_mask:0xf bank_mask:0xf
	v_mov_b32_dpp v195, v93 row_ror:15 row_mask:0xf bank_mask:0xf
	v_mov_b32_dpp v196, v94 row_ror:15 row_mask:0xf bank_mask:0xf
	v_mov_b32_dpp v197, v95 row_ror:15 row_mask:0xf bank_mask:0xf
	v_mov_b32_dpp v150, v92 row_ror:1 row_mask:0xf bank_mask:0xf
	v_mov_b32_dpp v151, v93 row_ror:1 row_mask:0xf bank_mask:0xf
	v_mov_b32_dpp v152, v94 row_ror:1 row_mask:0xf bank_mask:0xf
	v_mov_b32_dpp v153, v95 row_ror:1 row_mask:0xf bank_mask:0xf
	v_mov_b32_dpp v198, v84 row_ror:15 row_mask:0xf bank_mask:0xf
	v_mov_b32_dpp v199, v85 row_ror:15 row_mask:0xf bank_mask:0xf
	v_mov_b32_dpp v200, v86 row_ror:15 row_mask:0xf bank_mask:0xf
	v_mov_b32_dpp v201, v87 row_ror:15 row_mask:0xf bank_mask:0xf
	s_waitcnt lgkmcnt(0)
	v_cndmask_b32_e64 v202, v150, v146, s[8:9]
	v_cndmask_b32_e64 v203, v151, v147, s[8:9]
	v_cndmask_b32_e64 v204, v152, v148, s[8:9]
	v_cndmask_b32_e64 v205, v153, v149, s[8:9]
	s_cmp_eq_u32 s7, 0
	s_cbranch_scc0 .LffnB_bz_4
	ds_read_b128 v[146:149], v170 offset:4096
	s_branch .LffnB_bj_5

; DEV unsigned cvt_pk_bf16(float lo, float hi) { unsigned r; asm volatile("v_cvt_pk_bf16_f32 %0, %1, %2" : "=v"(r) : "v"(lo), "v"(hi)); return r; }
; #define ROR1(x) __int_as_float(__builtin_amdgcn_update_dpp(0, __float_as_int(x), 0x121, 0xf, 0xf, false))
; #define ROR15(x) __int_as_float(__builtin_amdgcn_update_dpp(0, __float_as_int(x), 0x12F, 0xf, 0xf, false))
;     DEV void operator()(const Acc& acc, const Unit& u, int wr, int wc, int fr, int fq, LAS unsigned char* misc) const {
;     ...
;                 for (int m = 0; m < 4; ++m) {
;                     f32x4 Rm, Dnext = bdn;
; #pragma unroll
;                     for (int e = 0; e < 4; ++e) { Rm[e] = ROR1(acc[ai][0][m][n][e]); if (m < 3) Dnext[e] = ROR15(acc[ai][0][m < 3 ? m + 1 : 3][n][e]); }
;                     const f32x4 up = (fr > 0) ? Rm : Rprev;
;                     const f32x4 dn = (fr < 15) ? Dcur : Dnext;
;                     Rprev = Rm; Dcur = Dnext;
;                     const int rr = q * 64 + m * 16 + fr, sq = s0 + rr;
;                     const f32x4 g = acc[ai][0][m][n], v = acc[ai][1][m][n];
;                     f32x4 o;
; #pragma unroll
;                     for (int e = 0; e < 4; ++e) { const float z = w0[e] * up[e] + w1[e] * g[e] + w2[e] * dn[e] + bb[e]; o[e] = z * __builtin_amdgcn_rcpf(1.f + __builtin_amdgcn_exp2f(-1.4426950408889634f * z)) * v[e]; }
;                     if (rr >= 1 && rr <= 254) { u32x2 w; w.x = cvt_pk_bf16(o[0], o[1]); w.y = cvt_pk_bf16(o[2], o[3]);
;                         *(u32x2*)(act + (size_t)(sbase + sq) * DFF + j) = w; }
;                     if (rr < 2 || rr > 253) { const int rid = rr < 2 ? rr : rr - 252; *(f32x4*)(sbp + (size_t)rid * DFF + j) = g;
;                         if (rr == 0 || rr == 255) *(f32x4*)(sbp + (size_t)(4 + (rr == 255)) * DFF + j) = v; }
.LffnB_bj_5:
	v_cndmask_b32_e64 v206, v194, v198, s[10:11]
	v_cndmask_b32_e64 v207, v195, v199, s[10:11]
	v_cndmask_b32_e64 v208, v196, v200, s[10:11]
	v_cndmask_b32_e64 v209, v197, v201, s[10:11]
	v_mul_f32_e32 v92, v110, v92
	v_mul_f32_e32 v93, v111, v93
	v_mul_f32_e32 v94, v112, v94
	v_mul_f32_e32 v95, v113, v95
	v_mul_f32_e32 v206, v114, v206
	v_mul_f32_e32 v207, v115, v207
	v_mul_f32_e32 v208, v116, v208
	v_mul_f32_e32 v209, v117, v209
	v_fmac_f32_e32 v92, v106, v202
	v_fmac_f32_e32 v93, v107, v203
	v_fmac_f32_e32 v94, v108, v204
	v_fmac_f32_e32 v95, v109, v205
	v_add_f32_e32 v92, v206, v92
	v_add_f32_e32 v93, v207, v93
	v_add_f32_e32 v94, v208, v94
	v_add_f32_e32 v95, v209, v95
	v_add_f32_e32 v92, v118, v92
	v_add_f32_e32 v93, v119, v93
	v_add_f32_e32 v94, v120, v94
	v_add_f32_e32 v95, v121, v95
	v_mul_f32_e32 v202, 0xbfb8aa3b, v92
	v_mul_f32_e32 v203, 0xbfb8aa3b, v93
	v_mul_f32_e32 v204, 0xbfb8aa3b, v94
	v_mul_f32_e32 v205, 0xbfb8aa3b, v95
	v_exp_f32_e32 v202, v202
	v_exp_f32_e32 v203, v203
	v_exp_f32_e32 v204, v204
	v_exp_f32_e32 v205, v205
	v_add_f32_e32 v202, 1.0, v202
	v_add_f32_e32 v203, 1.0, v203
	v_add_f32_e32 v204, 1.0, v204
	v_add_f32_e32 v205, 1.0, v205
	v_rcp_f32_e32 v202, v202
	v_rcp_f32_e32 v203, v203
	v_rcp_f32_e32 v204, v204
	v_rcp_f32_e32 v205, v205
	v_mul_f32_e32 v92, v92, v202
	v_mul_f32_e32 v93, v93, v203
	v_mul_f32_e32 v94, v94, v204
	v_mul_f32_e32 v95, v95, v205
	v_mul_f32_e32 v92, v88, v92
	v_mul_f32_e32 v93, v89, v93
	v_mul_f32_e32 v94, v90, v94
	v_mul_f32_e32 v95, v91, v95
	v_cvt_pk_bf16_f32 v88, v92, v93
	v_cvt_pk_bf16_f32 v89, v94, v95
	v_mov_b32_dpp v190, v84 row_ror:1 row_mask:0xf bank_mask:0xf
	v_mov_b32_dpp v191, v85 row_ror:1 row_mask:0xf bank_mask:0xf
	v_mov_b32_dpp v192, v86 row_ror:1 row_mask:0xf bank_mask:0xf
	v_mov_b32_dpp v193, v87 row_ror:1 row_mask:0xf bank_mask:0xf
	v_mov_b32_dpp v194, v76 row_ror:15 row_mask:0xf bank_mask:0xf
	v_mov_b32_dpp v195, v77 row_ror:15 row_mask:0xf bank_mask:0xf
	v_mov_b32_dpp v196, v78 row_ror:15 row_mask:0xf bank_mask:0xf
	v_mov_b32_dpp v197, v79 row_ror:15 row_mask:0xf bank_mask:0xf
	v_cndmask_b32_e64 v202, v190, v150, s[8:9]
	v_cndmask_b32_e64 v203, v191, v151, s[8:9]
	v_cndmask_b32_e64 v204, v192, v152, s[8:9]
	v_cndmask_b32_e64 v205, v193, v153, s[8:9]
	v_cndmask_b32_e64 v206, v198, v194, s[10:11]
	v_cndmask_b32_e64 v207, v199, v195, s[10:11]
	v_cndmask_b32_e64 v208, v200, v196, s[10:11]
	v_cndmask_b32_e64 v209, v201, v197, s[10:11]
	v_mul_f32_e32 v84, v110, v84
	v_mul_f32_e32 v85, v111, v85
	v_mul_f32_e32 v86, v112, v86
	v_mul_f32_e32 v87, v113, v87
	v_mul_f32_e32 v206, v114, v206
	v_mul_f32_e32 v207, v115, v207
	v_mul_f32_e32 v208, v116, v208
	v_mul_f32_e32 v209, v117, v209
	v_fmac_f32_e32 v84, v106, v202
	v_fmac_f32_e32 v85, v107, v203
	v_fmac_f32_e32 v86, v108, v204
	v_fmac_f32_e32 v87, v109, v205
	v_add_f32_e32 v84, v206, v84
	v_add_f32_e32 v85, v207, v85
	v_add_f32_e32 v86, v208, v86
	v_add_f32_e32 v87, v209, v87
	v_add_f32_e32 v84, v118, v84
	v_add_f32_e32 v85, v119, v85
	v_add_f32_e32 v86, v120, v86
	v_add_f32_e32 v87, v121, v87
	v_mul_f32_e32 v202, 0xbfb8aa3b, v84
	v_mul_f32_e32 v203, 0xbfb8aa3b, v85
	v_mul_f32_e32 v204, 0xbfb8aa3b, v86
	v_mul_f32_e32 v205, 0xbfb8aa3b, v87
	v_exp_f32_e32 v202, v202
	v_exp_f32_e32 v203, v203
	v_exp_f32_e32 v204, v204
	v_exp_f32_e32 v205, v205
	v_add_f32_e32 v202, 1.0, v202
	v_add_f32_e32 v203, 1.0, v203
	v_add_f32_e32 v204, 1.0, v204
	v_add_f32_e32 v205, 1.0, v205
	v_rcp_f32_e32 v202, v202
	v_rcp_f32_e32 v203, v203
	v_rcp_f32_e32 v204, v204
	v_rcp_f32_e32 v205, v205
	v_mul_f32_e32 v84, v84, v202
	v_mul_f32_e32 v85, v85, v203
	v_mul_f32_e32 v86, v86, v204
	v_mul_f32_e32 v87, v87, v205
	v_mul_f32_e32 v84, v80, v84
	v_mul_f32_e32 v85, v81, v85
	v_mul_f32_e32 v86, v82, v86
	v_mul_f32_e32 v87, v83, v87
	v_cvt_pk_bf16_f32 v80, v84, v85
	v_cvt_pk_bf16_f32 v81, v86, v87
	v_mov_b32_dpp v150, v76 row_ror:1 row_mask:0xf bank_mask:0xf
	v_mov_b32_dpp v151, v77 row_ror:1 row_mask:0xf bank_mask:0xf
	v_mov_b32_dpp v152, v78 row_ror:1 row_mask:0xf bank_mask:0xf
	v_mov_b32_dpp v153, v79 row_ror:1 row_mask:0xf bank_mask:0xf
	v_mov_b32_dpp v198, v68 row_ror:15 row_mask:0xf bank_mask:0xf
	v_mov_b32_dpp v199, v69 row_ror:15 row_mask:0xf bank_mask:0xf
	v_mov_b32_dpp v200, v70 row_ror:15 row_mask:0xf bank_mask:0xf
	v_mov_b32_dpp v201, v71 row_ror:15 row_mask:0xf bank_mask:0xf
	v_cndmask_b32_e64 v202, v150, v190, s[8:9]
	v_cndmask_b32_e64 v203, v151, v191, s[8:9]
	v_cndmask_b32_e64 v204, v152, v192, s[8:9]
	v_cndmask_b32_e64 v205, v153, v193, s[8:9]
	v_cndmask_b32_e64 v206, v194, v198, s[10:11]
	v_cndmask_b32_e64 v207, v195, v199, s[10:11]
	v_cndmask_b32_e64 v208, v196, v200, s[10:11]
	v_cndmask_b32_e64 v209, v197, v201, s[10:11]
	v_mul_f32_e32 v76, v110, v76
	v_mul_f32_e32 v77, v111, v77
	v_mul_f32_e32 v78, v112, v78
	v_mul_f32_e32 v79, v113, v79
	v_mul_f32_e32 v206, v114, v206
	v_mul_f32_e32 v207, v115, v207
	v_mul_f32_e32 v208, v116, v208
	v_mul_f32_e32 v209, v117, v209
	v_fmac_f32_e32 v76, v106, v202
	v_fmac_f32_e32 v77, v107, v203
	v_fmac_f32_e32 v78, v108, v204
	v_fmac_f32_e32 v79, v109, v205
	v_add_f32_e32 v76, v206, v76
	v_add_f32_e32 v77, v207, v77
	v_add_f32_e32 v78, v208, v78
	v_add_f32_e32 v79, v209, v79
	v_add_f32_e32 v76, v118, v76
	v_add_f32_e32 v77, v119, v77
	v_add_f32_e32 v78, v120, v78
	v_add_f32_e32 v79, v121, v79
	v_mul_f32_e32 v202, 0xbfb8aa3b, v76
	v_mul_f32_e32 v203, 0xbfb8aa3b, v77
	v_mul_f32_e32 v204, 0xbfb8aa3b, v78
	v_mul_f32_e32 v205, 0xbfb8aa3b, v79
	v_exp_f32_e32 v202, v202
	v_exp_f32_e32 v203, v203
	v_exp_f32_e32 v204, v204
	v_exp_f32_e32 v205, v205
	v_add_f32_e32 v202, 1.0, v202
	v_add_f32_e32 v203, 1.0, v203
	v_add_f32_e32 v204, 1.0, v204
	v_add_f32_e32 v205, 1.0, v205
	v_rcp_f32_e32 v202, v202
	v_rcp_f32_e32 v203, v203
	v_rcp_f32_e32 v204, v204
	v_rcp_f32_e32 v205, v205
	v_mul_f32_e32 v76, v76, v202
	v_mul_f32_e32 v77, v77, v203
	v_mul_f32_e32 v78, v78, v204
	v_mul_f32_e32 v79, v79, v205
	v_mul_f32_e32 v76, v72, v76
	v_mul_f32_e32 v77, v73, v77
	v_mul_f32_e32 v78, v74, v78
	v_mul_f32_e32 v79, v75, v79
	v_cvt_pk_bf16_f32 v72, v76, v77
	v_cvt_pk_bf16_f32 v73, v78, v79
	s_cmp_eq_u32 s7, 1
	s_cbranch_scc0 .LffnB_ns_6
	v_mul_u32_u24_e32 v171, 0x2c00, v166
	v_cmp_lt_u32_e64 s[30:31], 13, v166
	v_add_u32_e32 v171, v171, v167
	v_add_u32_e32 v171, 0xfffdf000, v171
	s_nop 1
	s_mov_b64 exec, s[30:31]
	global_store_dwordx4 v171, v[68:71], s[24:25]
	s_mov_b64 exec, s[10:11]
	global_store_dwordx4 v171, v[64:67], s[28:29]
	s_mov_b64 exec, -1
	s_nop 4
; DEV unsigned cvt_pk_bf16(float lo, float hi) { unsigned r; asm volatile("v_cvt_pk_bf16_f32 %0, %1, %2" : "=v"(r) : "v"(lo), "v"(hi)); return r; }
; #define ROR1(x) __int_as_float(__builtin_amdgcn_update_dpp(0, __float_as_int(x), 0x121, 0xf, 0xf, false))
; #define ROR15(x) __int_as_float(__builtin_amdgcn_update_dpp(0, __float_as_int(x), 0x12F, 0xf, 0xf, false))
;     DEV void operator()(const Acc& acc, const Unit& u, int wr, int wc, int fr, int fq, LAS unsigned char* misc) const {
;     ...
;                 for (int m = 0; m < 4; ++m) {
;                     f32x4 Rm, Dnext = bdn;
; #pragma unroll
;                     for (int e = 0; e < 4; ++e) { Rm[e] = ROR1(acc[ai][0][m][n][e]); if (m < 3) Dnext[e] = ROR15(acc[ai][0][m < 3 ? m + 1 : 3][n][e]); }
;                     const f32x4 up = (fr > 0) ? Rm : Rprev;
;                     const f32x4 dn = (fr < 15) ? Dcur : Dnext;
;                     Rprev = Rm; Dcur = Dnext;
;                     const int rr = q * 64 + m * 16 + fr, sq = s0 + rr;
;                     const f32x4 g = acc[ai][0][m][n], v = acc[ai][1][m][n];
;                     f32x4 o;
; #pragma unroll
;                     for (int e = 0; e < 4; ++e) { const float z = w0[e] * up[e] + w1[e] * g[e] + w2[e] * dn[e] + bb[e]; o[e] = z * __builtin_amdgcn_rcpf(1.f + __builtin_amdgcn_exp2f(-1.4426950408889634f * z)) * v[e]; }
;                     if (rr >= 1 && rr <= 254) { u32x2 w; w.x = cvt_pk_bf16(o[0], o[1]); w.y = cvt_pk_bf16(o[2], o[3]);
;                         *(u32x2*)(act + (size_t)(sbase + sq) * DFF + j) = w; }
.LffnB_ns_6:
	v_mov_b32_dpp v190, v68 row_ror:1 row_mask:0xf bank_mask:0xf
	v_mov_b32_dpp v191, v69 row_ror:1 row_mask:0xf bank_mask:0xf
	v_mov_b32_dpp v192, v70 row_ror:1 row_mask:0xf bank_mask:0xf
	v_mov_b32_dpp v193, v71 row_ror:1 row_mask:0xf bank_mask:0xf
	v_cndmask_b32_e64 v202, v190, v150, s[8:9]
	v_cndmask_b32_e64 v203, v191, v151, s[8:9]
	v_cndmask_b32_e64 v204, v192, v152, s[8:9]
	v_cndmask_b32_e64 v205, v193, v153, s[8:9]
	s_waitcnt lgkmcnt(0)
	v_cndmask_b32_e64 v206, v198, v146, s[10:11]
	v_cndmask_b32_e64 v207, v199, v147, s[10:11]
	v_cndmask_b32_e64 v208, v200, v148, s[10:11]
	v_cndmask_b32_e64 v209, v201, v149, s[10:11]
	v_mul_f32_e32 v68, v110, v68
	v_mul_f32_e32 v69, v111, v69
	v_mul_f32_e32 v70, v112, v70
	v_mul_f32_e32 v71, v113, v71
	v_mul_f32_e32 v206, v114, v206
	v_mul_f32_e32 v207, v115, v207
	v_mul_f32_e32 v208, v116, v208
	v_mul_f32_e32 v209, v117, v209
	v_fmac_f32_e32 v68, v106, v202
	v_fmac_f32_e32 v69, v107, v203
	v_fmac_f32_e32 v70, v108, v204
	v_fmac_f32_e32 v71, v109, v205
	v_add_f32_e32 v68, v206, v68
	v_add_f32_e32 v69, v207, v69
	v_add_f32_e32 v70, v208, v70
	v_add_f32_e32 v71, v209, v71
	v_add_f32_e32 v68, v118, v68
	v_add_f32_e32 v69, v119, v69
	v_add_f32_e32 v70, v120, v70
	v_add_f32_e32 v71, v121, v71
	v_mul_f32_e32 v202, 0xbfb8aa3b, v68
	v_mul_f32_e32 v203, 0xbfb8aa3b, v69
	v_mul_f32_e32 v204, 0xbfb8aa3b, v70
	v_mul_f32_e32 v205, 0xbfb8aa3b, v71
	v_exp_f32_e32 v202, v202
	v_exp_f32_e32 v203, v203
	v_exp_f32_e32 v204, v204
	v_exp_f32_e32 v205, v205
	v_add_f32_e32 v202, 1.0, v202
	v_add_f32_e32 v203, 1.0, v203
	v_add_f32_e32 v204, 1.0, v204
	v_add_f32_e32 v205, 1.0, v205
	v_rcp_f32_e32 v202, v202
	v_rcp_f32_e32 v203, v203
	v_rcp_f32_e32 v204, v204
	v_rcp_f32_e32 v205, v205
	v_mul_f32_e32 v68, v68, v202
	v_mul_f32_e32 v69, v69, v203
	v_mul_f32_e32 v70, v70, v204
	v_mul_f32_e32 v71, v71, v205
	v_mul_f32_e32 v68, v64, v68
	v_mul_f32_e32 v69, v65, v69
	v_mul_f32_e32 v70, v66, v70
	v_mul_f32_e32 v71, v67, v71
	v_cvt_pk_bf16_f32 v64, v68, v69
	v_cvt_pk_bf16_f32 v65, v70, v71
	s_cmp_eq_u32 s7, 0
	s_cbranch_scc1 .LffnB_bz_7
	ds_read_b128 v[146:149], v170 offset:16
	s_branch .LffnB_bj_8

; #define LAS __attribute__((address_space(3)))
; DEV unsigned cvt_pk_bf16(float lo, float hi) { unsigned r; asm volatile("v_cvt_pk_bf16_f32 %0, %1, %2" : "=v"(r) : "v"(lo), "v"(hi)); return r; }
;     DEV void operator()(const Acc& acc, const Unit& u, int wr, int wc, int fr, int fq, LAS unsigned char* misc) const {
;     ...
;         for (int n = 0; n < 2; ++n) { const int cc = wc * 32 + 8 * fq + 4 * n, j = u.pn * 128 + cc;
;             const f32x4 w0 = *(const f32x4*)(cw + j), w1 = *(const f32x4*)(cw + DFF + j), w2 = *(const f32x4*)(cw + 2 * DFF + j), bb = *(const f32x4*)(cb + j);
; #pragma unroll
;             for (int ai = 0; ai < 2; ++ai) { const int q = 2 * ai + wr;
;                 const f32x4 bup = (q > 0) ? *(LAS f32x4*)(xl + (q - 1) * 128 + cc) : (f32x4){0.f, 0.f, 0.f, 0.f};
;                 const f32x4 bdn = (q < 3) ? *(LAS f32x4*)(xf + (q + 1) * 128 + cc) : (f32x4){0.f, 0.f, 0.f, 0.f};
;                 f32x4 Rprev = bup, Dcur;
; #pragma unroll
;                 for (int e = 0; e < 4; ++e) Dcur[e] = ROR15(acc[ai][0][0][n][e]);
; #pragma unroll
;                 for (int m = 0; m < 4; ++m) {
;                     f32x4 Rm, Dnext = bdn;
; #pragma unroll
;                     for (int e = 0; e < 4; ++e) { Rm[e] = ROR1(acc[ai][0][m][n][e]); if (m < 3) Dnext[e] = ROR15(acc[ai][0][m < 3 ? m + 1 : 3][n][e]); }
;                     const f32x4 up = (fr > 0) ? Rm : Rprev;
;                     const f32x4 dn = (fr < 15) ? Dcur : Dnext;
;                     Rprev = Rm; Dcur = Dnext;
;                     const int rr = q * 64 + m * 16 + fr, sq = s0 + rr;
;                     const f32x4 g = acc[ai][0][m][n], v = acc[ai][1][m][n];
;                     f32x4 o;
; #pragma unroll
;                     for (int e = 0; e < 4; ++e) { const float z = w0[e] * up[e] + w1[e] * g[e] + w2[e] * dn[e] + bb[e]; o[e] = z * __builtin_amdgcn_rcpf(1.f + __builtin_amdgcn_exp2f(-1.4426950408889634f * z)) * v[e]; }
;                     if (rr >= 1 && rr <= 254) { u32x2 w; w.x = cvt_pk_bf16(o[0], o[1]); w.y = cvt_pk_bf16(o[2], o[3]);
;                         *(u32x2*)(act + (size_t)(sbase + sq) * DFF + j) = w; }
;                     if (rr < 2 || rr > 253) { const int rid = rr < 2 ? rr : rr - 252; *(f32x4*)(sbp + (size_t)rid * DFF + j) = g;
;                         if (rr == 0 || rr == 255) *(f32x4*)(sbp + (size_t)(4 + (rr == 255)) * DFF + j) = v; }
.LffnB_bj_8:
	v_mov_b32_dpp v194, v56 row_ror:15 row_mask:0xf bank_mask:0xf
	v_mov_b32_dpp v195, v57 row_ror:15 row_mask:0xf bank_mask:0xf
	v_mov_b32_dpp v196, v58 row_ror:15 row_mask:0xf bank_mask:0xf
	v_mov_b32_dpp v197, v59 row_ror:15 row_mask:0xf bank_mask:0xf
	s_waitcnt vmcnt(0)
	s_cmp_eq_u32 s7, 0
	s_cbranch_scc0 .LffnB_ns_9
	v_mul_u32_u24_e32 v171, 0x2c00, v166
	v_cmp_gt_u32_e64 s[30:31], 2, v166
	v_add_u32_e32 v171, v171, v167
	s_nop 1
	s_mov_b64 exec, s[30:31]
	global_store_dwordx4 v171, v[56:59], s[24:25] offset:16
	s_mov_b64 exec, s[8:9]
	global_store_dwordx4 v171, v[60:63], s[26:27] offset:16
	s_mov_b64 exec, -1
	s_nop 4
.LffnB_ns_9:
	v_mov_b32_dpp v150, v56 row_ror:1 row_mask:0xf bank_mask:0xf
	v_mov_b32_dpp v151, v57 row_ror:1 row_mask:0xf bank_mask:0xf
	v_mov_b32_dpp v152, v58 row_ror:1 row_mask:0xf bank_mask:0xf
	v_mov_b32_dpp v153, v59 row_ror:1 row_mask:0xf bank_mask:0xf
	v_mov_b32_dpp v198, v52 row_ror:15 row_mask:0xf bank_mask:0xf
	v_mov_b32_dpp v199, v53 row_ror:15 row_mask:0xf bank_mask:0xf
	v_mov_b32_dpp v200, v54 row_ror:15 row_mask:0xf bank_mask:0xf
	v_mov_b32_dpp v201, v55 row_ror:15 row_mask:0xf bank_mask:0xf
	s_waitcnt lgkmcnt(0)
	v_cndmask_b32_e64 v202, v150, v146, s[8:9]
	v_cndmask_b32_e64 v203, v151, v147, s[8:9]
	v_cndmask_b32_e64 v204, v152, v148, s[8:9]
	v_cndmask_b32_e64 v205, v153, v149, s[8:9]
	ds_read_b128 v[146:149], v170 offset:3088
	v_cndmask_b32_e64 v206, v194, v198, s[10:11]
	v_cndmask_b32_e64 v207, v195, v199, s[10:11]
	v_cndmask_b32_e64 v208, v196, v200, s[10:11]
	v_cndmask_b32_e64 v209, v197, v201, s[10:11]
	v_mul_f32_e32 v56, v134, v56
	v_mul_f32_e32 v57, v135, v57
	v_mul_f32_e32 v58, v136, v58
	v_mul_f32_e32 v59, v137, v59
	v_mul_f32_e32 v206, v126, v206
	v_mul_f32_e32 v207, v127, v207
	v_mul_f32_e32 v208, v128, v208
	v_mul_f32_e32 v209, v129, v209
	v_fmac_f32_e32 v56, v138, v202
	v_fmac_f32_e32 v57, v139, v203
	v_fmac_f32_e32 v58, v140, v204
	v_fmac_f32_e32 v59, v141, v205
	v_add_f32_e32 v56, v206, v56
	v_add_f32_e32 v57, v207, v57
	v_add_f32_e32 v58, v208, v58
	v_add_f32_e32 v59, v209, v59
	v_add_f32_e32 v56, v98, v56
	v_add_f32_e32 v57, v99, v57
	v_add_f32_e32 v58, v100, v58
	v_add_f32_e32 v59, v101, v59
	v_mul_f32_e32 v202, 0xbfb8aa3b, v56
	v_mul_f32_e32 v203, 0xbfb8aa3b, v57
	v_mul_f32_e32 v204, 0xbfb8aa3b, v58
	v_mul_f32_e32 v205, 0xbfb8aa3b, v59
	v_exp_f32_e32 v202, v202
	v_exp_f32_e32 v203, v203
	v_exp_f32_e32 v204, v204
	v_exp_f32_e32 v205, v205
	v_add_f32_e32 v202, 1.0, v202
	v_add_f32_e32 v203, 1.0, v203
	v_add_f32_e32 v204, 1.0, v204
	v_add_f32_e32 v205, 1.0, v205
	v_rcp_f32_e32 v202, v202
	v_rcp_f32_e32 v203, v203
	v_rcp_f32_e32 v204, v204
	v_rcp_f32_e32 v205, v205
	v_mul_f32_e32 v56, v56, v202
	v_mul_f32_e32 v57, v57, v203
	v_mul_f32_e32 v58, v58, v204
	v_mul_f32_e32 v59, v59, v205
	v_mul_f32_e32 v56, v60, v56
	v_mul_f32_e32 v57, v61, v57
	v_mul_f32_e32 v58, v62, v58
	v_mul_f32_e32 v59, v63, v59
	v_cvt_pk_bf16_f32 v144, v56, v57
	v_cvt_pk_bf16_f32 v145, v58, v59
	v_add_u32_e32 v169, 0x0, v168
	s_mov_b64 exec, s[12:13]
	global_store_dwordx4 v169, v[142:145], s[18:19]
	s_mov_b64 exec, -1
	s_nop 4
	v_mov_b32_dpp v190, v52 row_ror:1 row_mask:0xf bank_mask:0xf
	v_mov_b32_dpp v191, v53 row_ror:1 row_mask:0xf bank_mask:0xf
	v_mov_b32_dpp v192, v54 row_ror:1 row_mask:0xf bank_mask:0xf
	v_mov_b32_dpp v193, v55 row_ror:1 row_mask:0xf bank_mask:0xf
	v_mov_b32_dpp v194, v44 row_ror:15 row_mask:0xf bank_mask:0xf
	v_mov_b32_dpp v195, v45 row_ror:15 row_mask:0xf bank_mask:0xf
	v_mov_b32_dpp v196, v46 row_ror:15 row_mask:0xf bank_mask:0xf
	v_mov_b32_dpp v197, v47 row_ror:15 row_mask:0xf bank_mask:0xf
	v_cndmask_b32_e64 v202, v190, v150, s[8:9]
	v_cndmask_b32_e64 v203, v191, v151, s[8:9]
	v_cndmask_b32_e64 v204, v192, v152, s[8:9]
	v_cndmask_b32_e64 v205, v193, v153, s[8:9]
	v_cndmask_b32_e64 v206, v198, v194, s[10:11]
	v_cndmask_b32_e64 v207, v199, v195, s[10:11]
	v_cndmask_b32_e64 v208, v200, v196, s[10:11]
	v_cndmask_b32_e64 v209, v201, v197, s[10:11]
	v_mul_f32_e32 v52, v134, v52
	v_mul_f32_e32 v53, v135, v53
	v_mul_f32_e32 v54, v136, v54
	v_mul_f32_e32 v55, v137, v55
	v_mul_f32_e32 v206, v126, v206
	v_mul_f32_e32 v207, v127, v207
	v_mul_f32_e32 v208, v128, v208
	v_mul_f32_e32 v209, v129, v209
	v_fmac_f32_e32 v52, v138, v202
	v_fmac_f32_e32 v53, v139, v203
	v_fmac_f32_e32 v54, v140, v204
	v_fmac_f32_e32 v55, v141, v205
	v_add_f32_e32 v52, v206, v52
	v_add_f32_e32 v53, v207, v53
	v_add_f32_e32 v54, v208, v54
	v_add_f32_e32 v55, v209, v55
	v_add_f32_e32 v52, v98, v52
	v_add_f32_e32 v53, v99, v53
	v_add_f32_e32 v54, v100, v54
	v_add_f32_e32 v55, v101, v55
	v_mul_f32_e32 v202, 0xbfb8aa3b, v52
	v_mul_f32_e32 v203, 0xbfb8aa3b, v53
	v_mul_f32_e32 v204, 0xbfb8aa3b, v54
	v_mul_f32_e32 v205, 0xbfb8aa3b, v55
	v_exp_f32_e32 v202, v202
	v_exp_f32_e32 v203, v203
	v_exp_f32_e32 v204, v204
	v_exp_f32_e32 v205, v205
	v_add_f32_e32 v202, 1.0, v202
	v_add_f32_e32 v203, 1.0, v203
	v_add_f32_e32 v204, 1.0, v204
	v_add_f32_e32 v205, 1.0, v205
	v_rcp_f32_e32 v202, v202
	v_rcp_f32_e32 v203, v203
	v_rcp_f32_e32 v204, v204
	v_rcp_f32_e32 v205, v205
	v_mul_f32_e32 v52, v52, v202
	v_mul_f32_e32 v53, v53, v203
	v_mul_f32_e32 v54, v54, v204
	v_mul_f32_e32 v55, v55, v205
	v_mul_f32_e32 v52, v48, v52
	v_mul_f32_e32 v53, v49, v53
	v_mul_f32_e32 v54, v50, v54
	v_mul_f32_e32 v55, v51, v55
	v_cvt_pk_bf16_f32 v132, v52, v53
	v_cvt_pk_bf16_f32 v133, v54, v55
	v_add_u32_e32 v169, 0x16000, v168
	global_store_dwordx4 v169, v[130:133], s[18:19]
	v_mov_b32_dpp v150, v44 row_ror:1 row_mask:0xf bank_mask:0xf
; DEV unsigned cvt_pk_bf16(float lo, float hi) { unsigned r; asm volatile("v_cvt_pk_bf16_f32 %0, %1, %2" : "=v"(r) : "v"(lo), "v"(hi)); return r; }
; #define ROR1(x) __int_as_float(__builtin_amdgcn_update_dpp(0, __float_as_int(x), 0x121, 0xf, 0xf, false))
; #define ROR15(x) __int_as_float(__builtin_amdgcn_update_dpp(0, __float_as_int(x), 0x12F, 0xf, 0xf, false))
;     DEV void operator()(const Acc& acc, const Unit& u, int wr, int wc, int fr, int fq, LAS unsigned char* misc) const {
;     ...
;                 for (int m = 0; m < 4; ++m) {
;                     f32x4 Rm, Dnext = bdn;
; #pragma unroll
;                     for (int e = 0; e < 4; ++e) { Rm[e] = ROR1(acc[ai][0][m][n][e]); if (m < 3) Dnext[e] = ROR15(acc[ai][0][m < 3 ? m + 1 : 3][n][e]); }
;                     const f32x4 up = (fr > 0) ? Rm : Rprev;
;                     const f32x4 dn = (fr < 15) ? Dcur : Dnext;
;                     Rprev = Rm; Dcur = Dnext;
;                     const int rr = q * 64 + m * 16 + fr, sq = s0 + rr;
;                     const f32x4 g = acc[ai][0][m][n], v = acc[ai][1][m][n];
;                     f32x4 o;
; #pragma unroll
;                     for (int e = 0; e < 4; ++e) { const float z = w0[e] * up[e] + w1[e] * g[e] + w2[e] * dn[e] + bb[e]; o[e] = z * __builtin_amdgcn_rcpf(1.f + __builtin_amdgcn_exp2f(-1.4426950408889634f * z)) * v[e]; }
;                     if (rr >= 1 && rr <= 254) { u32x2 w; w.x = cvt_pk_bf16(o[0], o[1]); w.y = cvt_pk_bf16(o[2], o[3]);
;                         *(u32x2*)(act + (size_t)(sbase + sq) * DFF + j) = w; }
	v_mov_b32_dpp v151, v45 row_ror:1 row_mask:0xf bank_mask:0xf
	v_mov_b32_dpp v152, v46 row_ror:1 row_mask:0xf bank_mask:0xf
	v_mov_b32_dpp v153, v47 row_ror:1 row_mask:0xf bank_mask:0xf
	v_mov_b32_dpp v198, v32 row_ror:15 row_mask:0xf bank_mask:0xf
	v_mov_b32_dpp v199, v33 row_ror:15 row_mask:0xf bank_mask:0xf
	v_mov_b32_dpp v200, v34 row_ror:15 row_mask:0xf bank_mask:0xf
	v_mov_b32_dpp v201, v35 row_ror:15 row_mask:0xf bank_mask:0xf
	v_cndmask_b32_e64 v202, v150, v190, s[8:9]
	v_cndmask_b32_e64 v203, v151, v191, s[8:9]
	v_cndmask_b32_e64 v204, v152, v192, s[8:9]
	v_cndmask_b32_e64 v205, v153, v193, s[8:9]
	v_cndmask_b32_e64 v206, v194, v198, s[10:11]
	v_cndmask_b32_e64 v207, v195, v199, s[10:11]
	v_cndmask_b32_e64 v208, v196, v200, s[10:11]
	v_cndmask_b32_e64 v209, v197, v201, s[10:11]
	v_mul_f32_e32 v44, v134, v44
	v_mul_f32_e32 v45, v135, v45
	v_mul_f32_e32 v46, v136, v46
	v_mul_f32_e32 v47, v137, v47
	v_mul_f32_e32 v206, v126, v206
	v_mul_f32_e32 v207, v127, v207
	v_mul_f32_e32 v208, v128, v208
	v_mul_f32_e32 v209, v129, v209
	v_fmac_f32_e32 v44, v138, v202
	v_fmac_f32_e32 v45, v139, v203
	v_fmac_f32_e32 v46, v140, v204
	v_fmac_f32_e32 v47, v141, v205
	v_add_f32_e32 v44, v206, v44
	v_add_f32_e32 v45, v207, v45
	v_add_f32_e32 v46, v208, v46
	v_add_f32_e32 v47, v209, v47
	v_add_f32_e32 v44, v98, v44
	v_add_f32_e32 v45, v99, v45
	v_add_f32_e32 v46, v100, v46
	v_add_f32_e32 v47, v101, v47
	v_mul_f32_e32 v202, 0xbfb8aa3b, v44
	v_mul_f32_e32 v203, 0xbfb8aa3b, v45
	v_mul_f32_e32 v204, 0xbfb8aa3b, v46
	v_mul_f32_e32 v205, 0xbfb8aa3b, v47
	v_exp_f32_e32 v202, v202
	v_exp_f32_e32 v203, v203
	v_exp_f32_e32 v204, v204
	v_exp_f32_e32 v205, v205
	v_add_f32_e32 v202, 1.0, v202
	v_add_f32_e32 v203, 1.0, v203
	v_add_f32_e32 v204, 1.0, v204
	v_add_f32_e32 v205, 1.0, v205
	v_rcp_f32_e32 v202, v202
	v_rcp_f32_e32 v203, v203
	v_rcp_f32_e32 v204, v204
	v_rcp_f32_e32 v205, v205
	v_mul_f32_e32 v44, v44, v202
	v_mul_f32_e32 v45, v45, v203
	v_mul_f32_e32 v46, v46, v204
	v_mul_f32_e32 v47, v47, v205
	v_mul_f32_e32 v44, v40, v44
	v_mul_f32_e32 v45, v41, v45
	v_mul_f32_e32 v46, v42, v46
	v_mul_f32_e32 v47, v43, v47
	v_cvt_pk_bf16_f32 v124, v44, v45
	v_cvt_pk_bf16_f32 v125, v46, v47
	v_add_u32_e32 v169, 0x2c000, v168
	global_store_dwordx4 v169, v[122:125], s[18:19]
	v_mov_b32_dpp v190, v32 row_ror:1 row_mask:0xf bank_mask:0xf
	v_mov_b32_dpp v191, v33 row_ror:1 row_mask:0xf bank_mask:0xf
	v_mov_b32_dpp v192, v34 row_ror:1 row_mask:0xf bank_mask:0xf
	v_mov_b32_dpp v193, v35 row_ror:1 row_mask:0xf bank_mask:0xf
	v_cndmask_b32_e64 v202, v190, v150, s[8:9]
	v_cndmask_b32_e64 v203, v191, v151, s[8:9]
	v_cndmask_b32_e64 v204, v192, v152, s[8:9]
	v_cndmask_b32_e64 v205, v193, v153, s[8:9]
	s_waitcnt lgkmcnt(0)
	v_cndmask_b32_e64 v206, v198, v146, s[10:11]
	v_cndmask_b32_e64 v207, v199, v147, s[10:11]
	v_cndmask_b32_e64 v208, v200, v148, s[10:11]
	v_cndmask_b32_e64 v209, v201, v149, s[10:11]
	v_mul_f32_e32 v32, v134, v32
	v_mul_f32_e32 v33, v135, v33
	v_mul_f32_e32 v34, v136, v34
	v_mul_f32_e32 v35, v137, v35
	v_mul_f32_e32 v206, v126, v206
	v_mul_f32_e32 v207, v127, v207
	v_mul_f32_e32 v208, v128, v208
	v_mul_f32_e32 v209, v129, v209
	v_fmac_f32_e32 v32, v138, v202
	v_fmac_f32_e32 v33, v139, v203
	v_fmac_f32_e32 v34, v140, v204
	v_fmac_f32_e32 v35, v141, v205
	v_add_f32_e32 v32, v206, v32
	v_add_f32_e32 v33, v207, v33
	v_add_f32_e32 v34, v208, v34
	v_add_f32_e32 v35, v209, v35
	v_add_f32_e32 v32, v98, v32
	v_add_f32_e32 v33, v99, v33
	v_add_f32_e32 v34, v100, v34
	v_add_f32_e32 v35, v101, v35
	v_mul_f32_e32 v202, 0xbfb8aa3b, v32
	v_mul_f32_e32 v203, 0xbfb8aa3b, v33
	v_mul_f32_e32 v204, 0xbfb8aa3b, v34
	v_mul_f32_e32 v205, 0xbfb8aa3b, v35
	v_exp_f32_e32 v202, v202
	v_exp_f32_e32 v203, v203
	v_exp_f32_e32 v204, v204
	v_exp_f32_e32 v205, v205
	v_add_f32_e32 v202, 1.0, v202
	v_add_f32_e32 v203, 1.0, v203
	v_add_f32_e32 v204, 1.0, v204
	v_add_f32_e32 v205, 1.0, v205
	v_rcp_f32_e32 v202, v202
	v_rcp_f32_e32 v203, v203
	v_rcp_f32_e32 v204, v204
	v_rcp_f32_e32 v205, v205
	v_mul_f32_e32 v32, v32, v202
	v_mul_f32_e32 v33, v33, v203
	v_mul_f32_e32 v34, v34, v204
	v_mul_f32_e32 v35, v35, v205
	v_mul_f32_e32 v32, v36, v32
	v_mul_f32_e32 v33, v37, v33
	v_mul_f32_e32 v34, v38, v34
	v_mul_f32_e32 v35, v39, v35
	v_cvt_pk_bf16_f32 v104, v32, v33
	v_cvt_pk_bf16_f32 v105, v34, v35
	v_add_u32_e32 v169, 0x42000, v168
	global_store_dwordx4 v169, v[102:105], s[18:19]
	ds_read_b128 v[146:149], v170 offset:1040
	v_mov_b32_dpp v194, v28 row_ror:15 row_mask:0xf bank_mask:0xf
	v_mov_b32_dpp v195, v29 row_ror:15 row_mask:0xf bank_mask:0xf
	v_mov_b32_dpp v196, v30 row_ror:15 row_mask:0xf bank_mask:0xf
	v_mov_b32_dpp v197, v31 row_ror:15 row_mask:0xf bank_mask:0xf
	v_mov_b32_dpp v150, v28 row_ror:1 row_mask:0xf bank_mask:0xf
	v_mov_b32_dpp v151, v29 row_ror:1 row_mask:0xf bank_mask:0xf
	v_mov_b32_dpp v152, v30 row_ror:1 row_mask:0xf bank_mask:0xf
	v_mov_b32_dpp v153, v31 row_ror:1 row_mask:0xf bank_mask:0xf
	v_mov_b32_dpp v198, v20 row_ror:15 row_mask:0xf bank_mask:0xf
	v_mov_b32_dpp v199, v21 row_ror:15 row_mask:0xf bank_mask:0xf
	v_mov_b32_dpp v200, v22 row_ror:15 row_mask:0xf bank_mask:0xf
	v_mov_b32_dpp v201, v23 row_ror:15 row_mask:0xf bank_mask:0xf
	s_waitcnt lgkmcnt(0)
	v_cndmask_b32_e64 v202, v150, v146, s[8:9]
	v_cndmask_b32_e64 v203, v151, v147, s[8:9]
	v_cndmask_b32_e64 v204, v152, v148, s[8:9]
	v_cndmask_b32_e64 v205, v153, v149, s[8:9]
	s_cmp_eq_u32 s7, 0
	s_cbranch_scc0 .LffnB_bz_10
	ds_read_b128 v[146:149], v170 offset:4112
	s_branch .LffnB_bj_11

; DEV unsigned cvt_pk_bf16(float lo, float hi) { unsigned r; asm volatile("v_cvt_pk_bf16_f32 %0, %1, %2" : "=v"(r) : "v"(lo), "v"(hi)); return r; }
; #define ROR1(x) __int_as_float(__builtin_amdgcn_update_dpp(0, __float_as_int(x), 0x121, 0xf, 0xf, false))
; #define ROR15(x) __int_as_float(__builtin_amdgcn_update_dpp(0, __float_as_int(x), 0x12F, 0xf, 0xf, false))
;     DEV void operator()(const Acc& acc, const Unit& u, int wr, int wc, int fr, int fq, LAS unsigned char* misc) const {
;     ...
;                 for (int m = 0; m < 4; ++m) {
;                     f32x4 Rm, Dnext = bdn;
; #pragma unroll
;                     for (int e = 0; e < 4; ++e) { Rm[e] = ROR1(acc[ai][0][m][n][e]); if (m < 3) Dnext[e] = ROR15(acc[ai][0][m < 3 ? m + 1 : 3][n][e]); }
;                     const f32x4 up = (fr > 0) ? Rm : Rprev;
;                     const f32x4 dn = (fr < 15) ? Dcur : Dnext;
;                     Rprev = Rm; Dcur = Dnext;
;                     const int rr = q * 64 + m * 16 + fr, sq = s0 + rr;
;                     const f32x4 g = acc[ai][0][m][n], v = acc[ai][1][m][n];
;                     f32x4 o;
; #pragma unroll
;                     for (int e = 0; e < 4; ++e) { const float z = w0[e] * up[e] + w1[e] * g[e] + w2[e] * dn[e] + bb[e]; o[e] = z * __builtin_amdgcn_rcpf(1.f + __builtin_amdgcn_exp2f(-1.4426950408889634f * z)) * v[e]; }
;                     if (rr >= 1 && rr <= 254) { u32x2 w; w.x = cvt_pk_bf16(o[0], o[1]); w.y = cvt_pk_bf16(o[2], o[3]);
;                         *(u32x2*)(act + (size_t)(sbase + sq) * DFF + j) = w; }
;                     if (rr < 2 || rr > 253) { const int rid = rr < 2 ? rr : rr - 252; *(f32x4*)(sbp + (size_t)rid * DFF + j) = g;
;                         if (rr == 0 || rr == 255) *(f32x4*)(sbp + (size_t)(4 + (rr == 255)) * DFF + j) = v; }
.LffnB_bj_11:
	v_cndmask_b32_e64 v206, v194, v198, s[10:11]
	v_cndmask_b32_e64 v207, v195, v199, s[10:11]
	v_cndmask_b32_e64 v208, v196, v200, s[10:11]
	v_cndmask_b32_e64 v209, v197, v201, s[10:11]
	v_mul_f32_e32 v28, v134, v28
	v_mul_f32_e32 v29, v135, v29
	v_mul_f32_e32 v30, v136, v30
	v_mul_f32_e32 v31, v137, v31
	v_mul_f32_e32 v206, v126, v206
	v_mul_f32_e32 v207, v127, v207
	v_mul_f32_e32 v208, v128, v208
	v_mul_f32_e32 v209, v129, v209
	v_fmac_f32_e32 v28, v138, v202
	v_fmac_f32_e32 v29, v139, v203
	v_fmac_f32_e32 v30, v140, v204
	v_fmac_f32_e32 v31, v141, v205
	v_add_f32_e32 v28, v206, v28
	v_add_f32_e32 v29, v207, v29
	v_add_f32_e32 v30, v208, v30
	v_add_f32_e32 v31, v209, v31
	v_add_f32_e32 v28, v98, v28
	v_add_f32_e32 v29, v99, v29
	v_add_f32_e32 v30, v100, v30
	v_add_f32_e32 v31, v101, v31
	v_mul_f32_e32 v202, 0xbfb8aa3b, v28
	v_mul_f32_e32 v203, 0xbfb8aa3b, v29
	v_mul_f32_e32 v204, 0xbfb8aa3b, v30
	v_mul_f32_e32 v205, 0xbfb8aa3b, v31
	v_exp_f32_e32 v202, v202
	v_exp_f32_e32 v203, v203
	v_exp_f32_e32 v204, v204
	v_exp_f32_e32 v205, v205
	v_add_f32_e32 v202, 1.0, v202
	v_add_f32_e32 v203, 1.0, v203
	v_add_f32_e32 v204, 1.0, v204
	v_add_f32_e32 v205, 1.0, v205
	v_rcp_f32_e32 v202, v202
	v_rcp_f32_e32 v203, v203
	v_rcp_f32_e32 v204, v204
	v_rcp_f32_e32 v205, v205
	v_mul_f32_e32 v28, v28, v202
	v_mul_f32_e32 v29, v29, v203
	v_mul_f32_e32 v30, v30, v204
	v_mul_f32_e32 v31, v31, v205
	v_mul_f32_e32 v28, v24, v28
	v_mul_f32_e32 v29, v25, v29
	v_mul_f32_e32 v30, v26, v30
	v_mul_f32_e32 v31, v27, v31
	v_cvt_pk_bf16_f32 v90, v28, v29
	v_cvt_pk_bf16_f32 v91, v30, v31
	v_add_u32_e32 v169, 0xb0000, v168
	global_store_dwordx4 v169, v[88:91], s[18:19]
	v_mov_b32_dpp v190, v20 row_ror:1 row_mask:0xf bank_mask:0xf
	v_mov_b32_dpp v191, v21 row_ror:1 row_mask:0xf bank_mask:0xf
	v_mov_b32_dpp v192, v22 row_ror:1 row_mask:0xf bank_mask:0xf
	v_mov_b32_dpp v193, v23 row_ror:1 row_mask:0xf bank_mask:0xf
	v_mov_b32_dpp v194, v12 row_ror:15 row_mask:0xf bank_mask:0xf
	v_mov_b32_dpp v195, v13 row_ror:15 row_mask:0xf bank_mask:0xf
	v_mov_b32_dpp v196, v14 row_ror:15 row_mask:0xf bank_mask:0xf
	v_mov_b32_dpp v197, v15 row_ror:15 row_mask:0xf bank_mask:0xf
	v_cndmask_b32_e64 v202, v190, v150, s[8:9]
	v_cndmask_b32_e64 v203, v191, v151, s[8:9]
	v_cndmask_b32_e64 v204, v192, v152, s[8:9]
	v_cndmask_b32_e64 v205, v193, v153, s[8:9]
	v_cndmask_b32_e64 v206, v198, v194, s[10:11]
	v_cndmask_b32_e64 v207, v199, v195, s[10:11]
	v_cndmask_b32_e64 v208, v200, v196, s[10:11]
	v_cndmask_b32_e64 v209, v201, v197, s[10:11]
	v_mul_f32_e32 v20, v134, v20
	v_mul_f32_e32 v21, v135, v21
	v_mul_f32_e32 v22, v136, v22
	v_mul_f32_e32 v23, v137, v23
	v_mul_f32_e32 v206, v126, v206
	v_mul_f32_e32 v207, v127, v207
	v_mul_f32_e32 v208, v128, v208
	v_mul_f32_e32 v209, v129, v209
	v_fmac_f32_e32 v20, v138, v202
	v_fmac_f32_e32 v21, v139, v203
	v_fmac_f32_e32 v22, v140, v204
	v_fmac_f32_e32 v23, v141, v205
	v_add_f32_e32 v20, v206, v20
	v_add_f32_e32 v21, v207, v21
	v_add_f32_e32 v22, v208, v22
	v_add_f32_e32 v23, v209, v23
	v_add_f32_e32 v20, v98, v20
	v_add_f32_e32 v21, v99, v21
	v_add_f32_e32 v22, v100, v22
	v_add_f32_e32 v23, v101, v23
	v_mul_f32_e32 v202, 0xbfb8aa3b, v20
	v_mul_f32_e32 v203, 0xbfb8aa3b, v21
	v_mul_f32_e32 v204, 0xbfb8aa3b, v22
	v_mul_f32_e32 v205, 0xbfb8aa3b, v23
	v_exp_f32_e32 v202, v202
	v_exp_f32_e32 v203, v203
	v_exp_f32_e32 v204, v204
	v_exp_f32_e32 v205, v205
	v_add_f32_e32 v202, 1.0, v202
	v_add_f32_e32 v203, 1.0, v203
	v_add_f32_e32 v204, 1.0, v204
	v_add_f32_e32 v205, 1.0, v205
	v_rcp_f32_e32 v202, v202
	v_rcp_f32_e32 v203, v203
	v_rcp_f32_e32 v204, v204
	v_rcp_f32_e32 v205, v205
	v_mul_f32_e32 v20, v20, v202
	v_mul_f32_e32 v21, v21, v203
	v_mul_f32_e32 v22, v22, v204
	v_mul_f32_e32 v23, v23, v205
	v_mul_f32_e32 v20, v16, v20
	v_mul_f32_e32 v21, v17, v21
	v_mul_f32_e32 v22, v18, v22
	v_mul_f32_e32 v23, v19, v23
	v_cvt_pk_bf16_f32 v82, v20, v21
	v_cvt_pk_bf16_f32 v83, v22, v23
	v_add_u32_e32 v169, 0xc6000, v168
	global_store_dwordx4 v169, v[80:83], s[18:19]
	v_mov_b32_dpp v150, v12 row_ror:1 row_mask:0xf bank_mask:0xf
	v_mov_b32_dpp v151, v13 row_ror:1 row_mask:0xf bank_mask:0xf
	v_mov_b32_dpp v152, v14 row_ror:1 row_mask:0xf bank_mask:0xf
	v_mov_b32_dpp v153, v15 row_ror:1 row_mask:0xf bank_mask:0xf
	v_mov_b32_dpp v198, v4 row_ror:15 row_mask:0xf bank_mask:0xf
	v_mov_b32_dpp v199, v5 row_ror:15 row_mask:0xf bank_mask:0xf
	v_mov_b32_dpp v200, v6 row_ror:15 row_mask:0xf bank_mask:0xf
	v_mov_b32_dpp v201, v7 row_ror:15 row_mask:0xf bank_mask:0xf
	v_cndmask_b32_e64 v202, v150, v190, s[8:9]
	v_cndmask_b32_e64 v203, v151, v191, s[8:9]
	v_cndmask_b32_e64 v204, v152, v192, s[8:9]
	v_cndmask_b32_e64 v205, v153, v193, s[8:9]
	v_cndmask_b32_e64 v206, v194, v198, s[10:11]
	v_cndmask_b32_e64 v207, v195, v199, s[10:11]
	v_cndmask_b32_e64 v208, v196, v200, s[10:11]
	v_cndmask_b32_e64 v209, v197, v201, s[10:11]
	v_mul_f32_e32 v12, v134, v12
	v_mul_f32_e32 v13, v135, v13
	v_mul_f32_e32 v14, v136, v14
	v_mul_f32_e32 v15, v137, v15
	v_mul_f32_e32 v206, v126, v206
	v_mul_f32_e32 v207, v127, v207
	v_mul_f32_e32 v208, v128, v208
	v_mul_f32_e32 v209, v129, v209
	v_fmac_f32_e32 v12, v138, v202
	v_fmac_f32_e32 v13, v139, v203
	v_fmac_f32_e32 v14, v140, v204
	v_fmac_f32_e32 v15, v141, v205
	v_add_f32_e32 v12, v206, v12
	v_add_f32_e32 v13, v207, v13
	v_add_f32_e32 v14, v208, v14
	v_add_f32_e32 v15, v209, v15
	v_add_f32_e32 v12, v98, v12
	v_add_f32_e32 v13, v99, v13
	v_add_f32_e32 v14, v100, v14
	v_add_f32_e32 v15, v101, v15
	v_mul_f32_e32 v202, 0xbfb8aa3b, v12
	v_mul_f32_e32 v203, 0xbfb8aa3b, v13
	v_mul_f32_e32 v204, 0xbfb8aa3b, v14
	v_mul_f32_e32 v205, 0xbfb8aa3b, v15
	v_exp_f32_e32 v202, v202
	v_exp_f32_e32 v203, v203
	v_exp_f32_e32 v204, v204
	v_exp_f32_e32 v205, v205
	v_add_f32_e32 v202, 1.0, v202
	v_add_f32_e32 v203, 1.0, v203
	v_add_f32_e32 v204, 1.0, v204
	v_add_f32_e32 v205, 1.0, v205
	v_rcp_f32_e32 v202, v202
	v_rcp_f32_e32 v203, v203
	v_rcp_f32_e32 v204, v204
	v_rcp_f32_e32 v205, v205
	v_mul_f32_e32 v12, v12, v202
	v_mul_f32_e32 v13, v13, v203
	v_mul_f32_e32 v14, v14, v204
	v_mul_f32_e32 v15, v15, v205
	v_mul_f32_e32 v12, v8, v12
	v_mul_f32_e32 v13, v9, v13
	v_mul_f32_e32 v14, v10, v14
	v_mul_f32_e32 v15, v11, v15
	v_cvt_pk_bf16_f32 v74, v12, v13
	v_cvt_pk_bf16_f32 v75, v14, v15
	v_add_u32_e32 v169, 0xdc000, v168
	global_store_dwordx4 v169, v[72:75], s[18:19]
	s_cmp_eq_u32 s7, 1
	s_cbranch_scc0 .LffnB_ns_12
	v_mul_u32_u24_e32 v171, 0x2c00, v166
	v_cmp_lt_u32_e64 s[30:31], 13, v166
	v_add_u32_e32 v171, v171, v167
	v_add_u32_e32 v171, 0xfffdf000, v171
	s_nop 1
	s_mov_b64 exec, s[30:31]
	global_store_dwordx4 v171, v[4:7], s[24:25] offset:16
	s_mov_b64 exec, s[10:11]
	global_store_dwordx4 v171, v[0:3], s[28:29] offset:16
	s_mov_b64 exec, -1
	s_nop 4
; DEV unsigned cvt_pk_bf16(float lo, float hi) { unsigned r; asm volatile("v_cvt_pk_bf16_f32 %0, %1, %2" : "=v"(r) : "v"(lo), "v"(hi)); return r; }
; #define ROR1(x) __int_as_float(__builtin_amdgcn_update_dpp(0, __float_as_int(x), 0x121, 0xf, 0xf, false))
; #define ROR15(x) __int_as_float(__builtin_amdgcn_update_dpp(0, __float_as_int(x), 0x12F, 0xf, 0xf, false))
;     DEV void operator()(const Acc& acc, const Unit& u, int wr, int wc, int fr, int fq, LAS unsigned char* misc) const {
;     ...
;                 for (int m = 0; m < 4; ++m) {
;                     f32x4 Rm, Dnext = bdn;
; #pragma unroll
;                     for (int e = 0; e < 4; ++e) { Rm[e] = ROR1(acc[ai][0][m][n][e]); if (m < 3) Dnext[e] = ROR15(acc[ai][0][m < 3 ? m + 1 : 3][n][e]); }
;                     const f32x4 up = (fr > 0) ? Rm : Rprev;
;                     const f32x4 dn = (fr < 15) ? Dcur : Dnext;
;                     Rprev = Rm; Dcur = Dnext;
;                     const int rr = q * 64 + m * 16 + fr, sq = s0 + rr;
;                     const f32x4 g = acc[ai][0][m][n], v = acc[ai][1][m][n];
;                     f32x4 o;
; #pragma unroll
;                     for (int e = 0; e < 4; ++e) { const float z = w0[e] * up[e] + w1[e] * g[e] + w2[e] * dn[e] + bb[e]; o[e] = z * __builtin_amdgcn_rcpf(1.f + __builtin_amdgcn_exp2f(-1.4426950408889634f * z)) * v[e]; }
;                     if (rr >= 1 && rr <= 254) { u32x2 w; w.x = cvt_pk_bf16(o[0], o[1]); w.y = cvt_pk_bf16(o[2], o[3]);
;                         *(u32x2*)(act + (size_t)(sbase + sq) * DFF + j) = w; }
;                     if (rr < 2 || rr > 253) { const int rid = rr < 2 ? rr : rr - 252; *(f32x4*)(sbp + (size_t)rid * DFF + j) = g;
;                         if (rr == 0 || rr == 255) *(f32x4*)(sbp + (size_t)(4 + (rr == 255)) * DFF + j) = v; }
;                 }
;                 asm volatile("" ::: "memory");
;             } }
.LffnB_ns_12:
	v_mov_b32_dpp v190, v4 row_ror:1 row_mask:0xf bank_mask:0xf
	v_mov_b32_dpp v191, v5 row_ror:1 row_mask:0xf bank_mask:0xf
	v_mov_b32_dpp v192, v6 row_ror:1 row_mask:0xf bank_mask:0xf
	v_mov_b32_dpp v193, v7 row_ror:1 row_mask:0xf bank_mask:0xf
	v_cndmask_b32_e64 v202, v190, v150, s[8:9]
	v_cndmask_b32_e64 v203, v191, v151, s[8:9]
	v_cndmask_b32_e64 v204, v192, v152, s[8:9]
	v_cndmask_b32_e64 v205, v193, v153, s[8:9]
	s_waitcnt lgkmcnt(0)
	v_cndmask_b32_e64 v206, v198, v146, s[10:11]
	v_cndmask_b32_e64 v207, v199, v147, s[10:11]
	v_cndmask_b32_e64 v208, v200, v148, s[10:11]
	v_cndmask_b32_e64 v209, v201, v149, s[10:11]
	v_mul_f32_e32 v4, v134, v4
	v_mul_f32_e32 v5, v135, v5
	v_mul_f32_e32 v6, v136, v6
	v_mul_f32_e32 v7, v137, v7
	v_mul_f32_e32 v206, v126, v206
	v_mul_f32_e32 v207, v127, v207
	v_mul_f32_e32 v208, v128, v208
	v_mul_f32_e32 v209, v129, v209
	v_fmac_f32_e32 v4, v138, v202
	v_fmac_f32_e32 v5, v139, v203
	v_fmac_f32_e32 v6, v140, v204
	v_fmac_f32_e32 v7, v141, v205
	v_add_f32_e32 v4, v206, v4
	v_add_f32_e32 v5, v207, v5
	v_add_f32_e32 v6, v208, v6
	v_add_f32_e32 v7, v209, v7
	v_add_f32_e32 v4, v98, v4
	v_add_f32_e32 v5, v99, v5
	v_add_f32_e32 v6, v100, v6
	v_add_f32_e32 v7, v101, v7
	v_mul_f32_e32 v202, 0xbfb8aa3b, v4
	v_mul_f32_e32 v203, 0xbfb8aa3b, v5
	v_mul_f32_e32 v204, 0xbfb8aa3b, v6
	v_mul_f32_e32 v205, 0xbfb8aa3b, v7
	v_exp_f32_e32 v202, v202
	v_exp_f32_e32 v203, v203
	v_exp_f32_e32 v204, v204
	v_exp_f32_e32 v205, v205
	v_add_f32_e32 v202, 1.0, v202
	v_add_f32_e32 v203, 1.0, v203
	v_add_f32_e32 v204, 1.0, v204
	v_add_f32_e32 v205, 1.0, v205
	v_rcp_f32_e32 v202, v202
	v_rcp_f32_e32 v203, v203
	v_rcp_f32_e32 v204, v204
	v_rcp_f32_e32 v205, v205
	v_mul_f32_e32 v4, v4, v202
	v_mul_f32_e32 v5, v5, v203
	v_mul_f32_e32 v6, v6, v204
	v_mul_f32_e32 v7, v7, v205
	v_mul_f32_e32 v4, v0, v4
	v_mul_f32_e32 v5, v1, v5
	v_mul_f32_e32 v6, v2, v6
	v_mul_f32_e32 v7, v3, v7
	v_cvt_pk_bf16_f32 v66, v4, v5
	v_cvt_pk_bf16_f32 v67, v6, v7
	v_add_u32_e32 v169, 0xf2000, v168
	s_mov_b64 exec, s[16:17]
	global_store_dwordx4 v169, v[64:67], s[18:19]
	s_mov_b64 exec, -1
	s_nop 4
	v_readlane_b32 s79, v249, 16
	s_and_b64 vcc, exec, s[2:3]
	s_mov_b64 s[2:3], -1
	s_cbranch_vccnz .LBB0_1745
	v_readlane_b32 s2, v251, 24
	v_readlane_b32 s3, v251, 25
	s_andn2_b64 vcc, exec, s[2:3]
	s_cbranch_vccnz .LBB0_1744
	s_barrier
	s_branch .LBB0_1744
